# v51 plus split-phase P3->P5 barrier for workgroups 128..255: arrive, run the half context unit (needs nothing P3 wrote), then wait for the release and run the GLU tile
# baseline (speedup 1.0000x reference)
.Lgb4_3_follow:
	s_cmp_gt_u32 s38, 0x7f
	s_cbranch_scc1 .LBB0_360
	v_mov_b32_e32 v2, 3
	s_mov_b32 s99, 0

.LBB0_378:
	s_add_i32 s3, s38, 0xffffff80
	s_cmpk_gt_i32 s38, 0x7f
	s_cselect_b32 s1, s3, 0x100000
	s_mov_b32 s98, s1
	v_mov_b32_e32 v13, v0
	v_readlane_b32 s94, v242, 40
	s_cmpk_gt_u32 s1, 0x7f
	v_readfirstlane_b32 s0, v13
	v_readlane_b32 s95, v242, 41
	s_cbranch_scc1 .LBB0_390
	s_branch .LBB0_386
.Lp5_glu:
	v_lshlrev_b32_e32 v1, 4, v13
	v_add_u32_e32 v2, 0x2000, v1
	v_ashrrev_i32_e32 v3, 31, v2
	v_lshrrev_b32_e32 v3, 22, v3
	v_add_u32_e32 v3, v2, v3
	v_ashrrev_i32_e32 v10, 10, v3
	v_mul_i32_i24_e32 v3, 0x400, v10
	v_sub_u32_e32 v2, v2, v3
	v_lshrrev_b32_e32 v3, 4, v2
	v_bitop3_b32 v2, v3, v2, 32 bitop3:0x6c
	v_ashrrev_i32_e32 v3, 31, v2
	v_lshrrev_b32_e32 v3, 26, v3
	v_add_u32_e32 v3, v2, v3
	v_lshlrev_b32_e32 v4, 3, v10
	v_ashrrev_i32_e32 v11, 6, v3
	v_and_b32_e32 v4, -16, v4
	v_add_u32_e32 v4, v11, v4
	v_and_b32_e32 v5, 3, v11
	s_mov_b32 s4, 0x3fffe0
	v_lshrrev_b32_e32 v6, 2, v4
	v_lshlrev_b32_e32 v7, 1, v4
	v_and_b32_e32 v3, 0xc0, v3
	v_and_or_b32 v5, v4, s4, v5
	v_and_b32_e32 v6, 4, v6
	v_and_b32_e32 v7, 24, v7
	v_sub_u32_e32 v2, v2, v3
	v_mov_b32_e32 v3, 1
	v_or3_b32 v5, v5, v6, v7
	v_lshlrev_b32_e32 v6, 5, v10
	v_ashrrev_i16_sdwa v2, v3, sext(v2) dst_sel:DWORD dst_unused:UNUSED_PAD src0_sel:DWORD src1_sel:BYTE_0
	v_and_b32_e32 v6, 32, v6
	v_bfe_i32 v12, v2, 0, 16
	v_add_lshl_u32 v2, v6, v12, 1
	v_lshl_add_u32 v58, v5, 10, v2
	v_lshl_add_u32 v60, v4, 10, v2
	v_add_u32_e32 v60, 0xffffc000, v60
	v_bfe_i32 v2, v13, 27, 1
	v_lshrrev_b32_e32 v2, 22, v2
	v_add_u32_e32 v2, v1, v2
	v_and_b32_e32 v2, 0xfffffc00, v2
	v_sub_u32_e32 v1, v1, v2
	v_lshrrev_b32_e32 v2, 4, v1
	v_ashrrev_i32_e32 v4, 31, v13
	v_bitop3_b32 v1, v2, v1, 32 bitop3:0x6c
	v_lshrrev_b32_e32 v4, 26, v4
	v_ashrrev_i32_e32 v2, 31, v1
	v_add_u32_e32 v4, v13, v4
	v_lshrrev_b32_e32 v2, 26, v2
	v_ashrrev_i32_e32 v15, 6, v4
	v_add_u32_e32 v2, v1, v2
	v_lshlrev_b32_e32 v4, 3, v15
	v_ashrrev_i32_e32 v14, 6, v2
	v_and_b32_e32 v4, -16, v4
	v_add_u32_e32 v4, v14, v4
	v_and_b32_e32 v5, 3, v14
	v_and_or_b32 v5, v4, s4, v5
	s_and_b32 s4, s1, 7
	s_lshr_b32 s1, s1, 3
	s_mul_i32 s4, s4, 12
	s_add_i32 s4, s4, s1
	s_and_b32 s1, s4, 0xff
	s_mulk_i32 s1, 0xab
	s_lshr_b32 s1, s1, 11
	s_mul_i32 s5, s1, 6
	s_mul_i32 s1, s1, 12
	s_sub_i32 s1, s4, s1
	s_and_b32 s4, s1, 0xff
	s_add_i32 s1, s1, 0xfffa
	s_and_b32 s1, s1, 0xff
	s_min_u32 s1, s4, s1
	s_add_i32 s1, s1, s5
	s_ashr_i32 s14, s0, 6
	s_and_b32 s1, s1, 0xff
	s_ashr_i32 s15, s0, 8
	s_and_b32 s1, s98, 7
	s_lshl_b32 s1, s1, 3
	s_lshr_b32 s99, s98, 4
	s_add_i32 s1, s1, s99
	s_mul_i32 s99, s1, 0xc0
	s_lshl_b32 s100, s15, 4
	s_sub_i32 s99, s99, s100
	s_lshl_b32 s20, s14, 10
	s_mul_i32 s16, s1, 0x30000
	s_bitcmp1_b32 s98, 3
	v_lshrrev_b32_e32 v6, 2, v4
	v_lshlrev_b32_e32 v7, 1, v4
	v_and_b32_e32 v2, 0xc0, v2
	s_cselect_b64 s[6:7], -1, 0
	v_and_b32_e32 v6, 4, v6
	v_and_b32_e32 v7, 24, v7
	v_sub_u32_e32 v1, v1, v2
	s_and_b64 s[4:5], s[6:7], exec
	v_or3_b32 v5, v5, v6, v7
	v_lshlrev_b32_e32 v6, 5, v15
	v_ashrrev_i16_sdwa v1, v3, sext(v1) dst_sel:DWORD dst_unused:UNUSED_PAD src0_sel:DWORD src1_sel:BYTE_0
	s_cselect_b32 s18, 0x40000, 0
	v_and_b32_e32 v6, 32, v6
	v_bfe_i32 v16, v1, 0, 16
	s_add_u32 s8, s84, s18
	v_add_lshl_u32 v1, v6, v16, 1
	s_addc_u32 s9, s85, 0
	s_add_i32 s4, s20, 0
	v_lshl_add_u32 v62, v5, 10, v1
	s_add_i32 m0, s4, 0x10000
	v_lshl_add_u32 v64, v4, 10, v1
	global_load_lds_dwordx4 v62, s[8:9]
	s_add_i32 m0, s4, 0x12000
	s_add_u32 s10, s8, 0x20000
	global_load_lds_dwordx4 v58, s[8:9]
	s_addc_u32 s11, s9, 0
	s_add_i32 m0, s4, 0x14000
	v_mov_b32_e32 v63, 0
	global_load_lds_dwordx4 v62, s[10:11]
	s_add_i32 m0, s4, 0x16000
	v_mov_b32_e32 v59, v63
	global_load_lds_dwordx4 v58, s[10:11]
	s_add_u32 s10, s80, s16
	s_addc_u32 s11, s81, 0
	s_add_i32 s5, s4, 0x2000
	s_mov_b32 m0, s4
	s_add_u32 s22, s10, 0x18000
	global_load_lds_dwordx4 v64, s[10:11]
	s_mov_b32 m0, s5
	s_addc_u32 s23, s11, 0
	s_add_i32 s24, s4, 0x4000
	global_load_lds_dwordx4 v60, s[10:11]
	s_mov_b32 m0, s24
	s_add_i32 s25, s4, 0x6000
	global_load_lds_dwordx4 v64, s[22:23]
	s_mov_b32 m0, s25
	v_mov_b32_e32 v65, v63
	global_load_lds_dwordx4 v60, s[22:23]
	v_mov_b32_e32 v61, v63
	v_lshl_add_u64 v[8:9], s[8:9], 0, v[62:63]
	v_lshl_add_u64 v[6:7], s[8:9], 0, v[58:59]
	v_lshl_add_u64 v[4:5], s[10:11], 0, v[64:65]
	s_cmp_lg_u32 s15, 1
	v_lshl_add_u64 v[2:3], s[10:11], 0, v[60:61]
	s_cbranch_scc1 .LBB0_381
	s_barrier

.LBB0_385:
	s_and_b64 s[4:5], s[6:7], exec
	s_cselect_b32 s0, 0x100, 0
	v_or_b32_e32 v58, s0, v78
	v_or_b32_e32 v60, s26, v58
	v_readlane_b32 s4, v242, 16
	v_lshlrev_b32_e32 v62, 2, v60
	v_readlane_b32 s12, v242, 24
	v_readlane_b32 s13, v242, 25
	s_nop 4
	global_load_dwordx4 v[74:77], v62, s[12:13] offset:16
	global_load_dwordx4 v[78:81], v62, s[12:13]
	v_add_u32_e32 v148, s99, v1
	v_ashrrev_i32_e32 v149, 31, v148
	v_lshlrev_b64 v[58:59], 10, v[148:149]
	v_lshl_add_u64 v[58:59], s[80:81], 0, v[58:59]
	v_lshlrev_b32_e32 v146, 1, v60
	v_mov_b32_e32 v147, 0
	v_lshl_add_u64 v[154:155], v[58:59], 0, v[146:147]
	global_load_dwordx4 v[150:153], v[154:155], off
	global_load_dwordx4 v[58:61], v62, s[12:13] offset:528
	s_nop 0
	global_load_dwordx4 v[62:65], v62, s[12:13] offset:512
	v_readlane_b32 s5, v242, 17
	v_readlane_b32 s6, v242, 18
	v_readlane_b32 s7, v242, 19
	v_readlane_b32 s8, v242, 20
	v_readlane_b32 s9, v242, 21
	v_readlane_b32 s10, v242, 22
	v_readlane_b32 s11, v242, 23
	v_readlane_b32 s14, v242, 26
	v_readlane_b32 s15, v242, 27
	v_readlane_b32 s16, v242, 28
	v_readlane_b32 s17, v242, 29
	v_readlane_b32 s18, v242, 30
	v_readlane_b32 s19, v242, 31
	s_waitcnt vmcnt(0)
	v_add_f32_e32 v138, v138, v74
	v_add_f32_e32 v1, v142, v78
	v_add_f32_e32 v142, v143, v79
	v_add_f32_e32 v139, v139, v75
	v_add_f32_e32 v143, v144, v80
	v_add_f32_e32 v140, v140, v76
	v_add_f32_e32 v144, v145, v81
	v_add_f32_e32 v141, v141, v77
	v_mul_f32_e32 v1, 0xbfb8aa3b, v1
	v_mul_f32_e32 v138, 0xbfb8aa3b, v138
	v_mul_f32_e32 v142, 0xbfb8aa3b, v142
	v_mul_f32_e32 v139, 0xbfb8aa3b, v139
	v_mul_f32_e32 v143, 0xbfb8aa3b, v143
	v_mul_f32_e32 v140, 0xbfb8aa3b, v140
	v_mul_f32_e32 v144, 0xbfb8aa3b, v144
	v_mul_f32_e32 v141, 0xbfb8aa3b, v141
	v_exp_f32_e32 v1, v1
	v_exp_f32_e32 v138, v138
	v_exp_f32_e32 v142, v142
	v_exp_f32_e32 v139, v139
	v_exp_f32_e32 v143, v143
	v_exp_f32_e32 v140, v140
	v_exp_f32_e32 v144, v144
	v_exp_f32_e32 v141, v141
	v_add_f32_e32 v1, 1.0, v1
	v_add_f32_e32 v138, 1.0, v138
	v_add_f32_e32 v142, 1.0, v142
	v_add_f32_e32 v139, 1.0, v139
	v_add_f32_e32 v143, 1.0, v143
	v_add_f32_e32 v140, 1.0, v140
	v_add_f32_e32 v144, 1.0, v144
	v_add_f32_e32 v141, 1.0, v141
	v_rcp_f32_e32 v1, v1
	v_rcp_f32_e32 v138, v138
	v_rcp_f32_e32 v142, v142
	v_rcp_f32_e32 v139, v139
	v_rcp_f32_e32 v143, v143
	v_rcp_f32_e32 v140, v140
	v_rcp_f32_e32 v144, v144
	v_rcp_f32_e32 v141, v141
	v_lshlrev_b32_e32 v145, 16, v150
	v_and_b32_e32 v150, 0xffff0000, v150
	v_lshlrev_b32_e32 v156, 16, v151
	v_and_b32_e32 v151, 0xffff0000, v151
	v_lshlrev_b32_e32 v157, 16, v152
	v_and_b32_e32 v152, 0xffff0000, v152
	v_lshlrev_b32_e32 v158, 16, v153
	v_and_b32_e32 v153, 0xffff0000, v153
	v_mul_f32_e32 v1, v1, v145
	v_mul_f32_e32 v145, v138, v157
	v_mul_f32_e32 v138, v142, v150
	v_mul_f32_e32 v142, v139, v152
	v_mul_f32_e32 v139, v143, v156
	v_mul_f32_e32 v143, v140, v158
	v_mul_f32_e32 v140, v144, v151
	v_mul_f32_e32 v141, v141, v153
	v_cvt_pk_bf16_f32 v138, v1, v138
	v_cvt_pk_bf16_f32 v139, v139, v140
	v_cvt_pk_bf16_f32 v140, v145, v142
	v_cvt_pk_bf16_f32 v141, v143, v141
	global_load_dwordx4 v[142:145], v[154:155], off offset:256
	v_add_f32_e32 v1, v134, v62
	v_add_f32_e32 v130, v130, v58
	v_add_f32_e32 v134, v135, v63
	v_add_f32_e32 v131, v131, v59
	v_add_f32_e32 v135, v136, v64
	v_add_f32_e32 v132, v132, v60
	v_add_f32_e32 v136, v137, v65
	v_add_f32_e32 v133, v133, v61
	v_mul_f32_e32 v1, 0xbfb8aa3b, v1
	v_mul_f32_e32 v130, 0xbfb8aa3b, v130
	v_mul_f32_e32 v134, 0xbfb8aa3b, v134
	v_mul_f32_e32 v131, 0xbfb8aa3b, v131
	v_mul_f32_e32 v135, 0xbfb8aa3b, v135
	v_mul_f32_e32 v132, 0xbfb8aa3b, v132
	v_mul_f32_e32 v136, 0xbfb8aa3b, v136
	v_mul_f32_e32 v133, 0xbfb8aa3b, v133
	v_exp_f32_e32 v1, v1
	v_exp_f32_e32 v130, v130
	v_exp_f32_e32 v134, v134
	v_exp_f32_e32 v131, v131
	v_exp_f32_e32 v135, v135
	v_exp_f32_e32 v132, v132
	v_exp_f32_e32 v136, v136
	v_exp_f32_e32 v133, v133
	v_add_f32_e32 v1, 1.0, v1
	v_add_f32_e32 v130, 1.0, v130
	v_add_f32_e32 v134, 1.0, v134
	v_add_f32_e32 v131, 1.0, v131
	v_add_f32_e32 v135, 1.0, v135
	v_add_f32_e32 v132, 1.0, v132
	v_add_f32_e32 v136, 1.0, v136
	v_add_f32_e32 v133, 1.0, v133
	v_add_u32_e32 v150, 16, v148
	v_lshlrev_b64 v[152:153], 11, v[148:149]
	v_rcp_f32_e32 v1, v1
	v_rcp_f32_e32 v130, v130
	v_rcp_f32_e32 v134, v134
	v_rcp_f32_e32 v131, v131
	v_rcp_f32_e32 v135, v135
	v_rcp_f32_e32 v132, v132
	v_rcp_f32_e32 v136, v136
	v_rcp_f32_e32 v133, v133
	v_ashrrev_i32_e32 v151, 31, v150
	v_lshl_add_u64 v[152:153], s[60:61], 0, v[152:153]
	v_lshlrev_b64 v[154:155], 10, v[150:151]
	v_lshl_add_u64 v[152:153], v[152:153], 0, v[146:147]
	v_lshl_add_u64 v[154:155], s[80:81], 0, v[154:155]
	global_store_dwordx4 v[152:153], v[138:141], off offset:1024
	v_lshl_add_u64 v[154:155], v[154:155], 0, v[146:147]
	v_add_f32_e32 v122, v122, v74
	v_add_f32_e32 v123, v123, v75
	v_add_f32_e32 v124, v124, v76
	v_add_f32_e32 v125, v125, v77
	v_mul_f32_e32 v122, 0xbfb8aa3b, v122
	v_mul_f32_e32 v123, 0xbfb8aa3b, v123
	v_mul_f32_e32 v124, 0xbfb8aa3b, v124
	v_mul_f32_e32 v125, 0xbfb8aa3b, v125
	v_exp_f32_e32 v122, v122
	v_exp_f32_e32 v123, v123
	v_exp_f32_e32 v124, v124
	v_exp_f32_e32 v125, v125
	v_add_f32_e32 v122, 1.0, v122
	v_add_f32_e32 v123, 1.0, v123
	v_add_f32_e32 v124, 1.0, v124
	v_add_f32_e32 v125, 1.0, v125
	v_rcp_f32_e32 v122, v122
	v_rcp_f32_e32 v123, v123
	v_rcp_f32_e32 v124, v124
	v_rcp_f32_e32 v125, v125
	v_add_f32_e32 v114, v114, v58
	v_add_f32_e32 v115, v115, v59
	v_add_f32_e32 v116, v116, v60
	v_add_f32_e32 v117, v117, v61
	v_mul_f32_e32 v114, 0xbfb8aa3b, v114
	v_mul_f32_e32 v115, 0xbfb8aa3b, v115
	v_mul_f32_e32 v116, 0xbfb8aa3b, v116
	v_mul_f32_e32 v117, 0xbfb8aa3b, v117
	v_exp_f32_e32 v114, v114
	v_exp_f32_e32 v115, v115
	s_waitcnt vmcnt(1)
	v_lshlrev_b32_e32 v137, 16, v142
	v_and_b32_e32 v138, 0xffff0000, v142
	v_lshlrev_b32_e32 v139, 16, v143
	v_and_b32_e32 v140, 0xffff0000, v143
	v_lshlrev_b32_e32 v141, 16, v144
	v_and_b32_e32 v142, 0xffff0000, v144
	v_lshlrev_b32_e32 v143, 16, v145
	v_and_b32_e32 v144, 0xffff0000, v145
	v_mul_f32_e32 v1, v1, v137
	v_mul_f32_e32 v137, v130, v141
	v_mul_f32_e32 v130, v134, v138
	v_mul_f32_e32 v134, v131, v142
	v_mul_f32_e32 v131, v135, v139
	v_mul_f32_e32 v135, v132, v143
	v_mul_f32_e32 v132, v136, v140
	v_mul_f32_e32 v133, v133, v144
	v_cvt_pk_bf16_f32 v130, v1, v130
	v_cvt_pk_bf16_f32 v131, v131, v132
	v_cvt_pk_bf16_f32 v132, v137, v134
	v_cvt_pk_bf16_f32 v133, v135, v133
	global_load_dwordx4 v[134:137], v[154:155], off
	v_add_f32_e32 v1, v126, v78
	v_add_f32_e32 v126, v127, v79
	v_add_f32_e32 v127, v128, v80
	v_add_f32_e32 v128, v129, v81
	v_mul_f32_e32 v1, 0xbfb8aa3b, v1
	v_mul_f32_e32 v126, 0xbfb8aa3b, v126
	v_mul_f32_e32 v127, 0xbfb8aa3b, v127
	v_mul_f32_e32 v128, 0xbfb8aa3b, v128
	v_exp_f32_e32 v1, v1
	v_exp_f32_e32 v126, v126
	v_exp_f32_e32 v127, v127
	v_exp_f32_e32 v128, v128
	v_add_f32_e32 v1, 1.0, v1
	v_add_f32_e32 v126, 1.0, v126
	v_add_f32_e32 v127, 1.0, v127
	v_add_f32_e32 v128, 1.0, v128
	v_rcp_f32_e32 v1, v1
	v_rcp_f32_e32 v126, v126
	v_rcp_f32_e32 v127, v127
	v_rcp_f32_e32 v128, v128
	global_store_dwordx4 v[152:153], v[130:133], off offset:1280
	v_exp_f32_e32 v116, v116
	v_exp_f32_e32 v117, v117
	v_add_f32_e32 v114, 1.0, v114
	v_add_f32_e32 v115, 1.0, v115
	v_add_f32_e32 v116, 1.0, v116
	v_add_f32_e32 v117, 1.0, v117
	v_rcp_f32_e32 v114, v114
	v_rcp_f32_e32 v115, v115
	v_rcp_f32_e32 v116, v116
	v_rcp_f32_e32 v117, v117
	v_add_f32_e32 v106, v106, v74
	v_add_f32_e32 v107, v107, v75
	v_add_f32_e32 v108, v108, v76
	v_add_f32_e32 v109, v109, v77
	v_mul_f32_e32 v106, 0xbfb8aa3b, v106
	v_mul_f32_e32 v107, 0xbfb8aa3b, v107
	v_mul_f32_e32 v108, 0xbfb8aa3b, v108
	v_mul_f32_e32 v109, 0xbfb8aa3b, v109
	v_exp_f32_e32 v106, v106
	v_exp_f32_e32 v107, v107
	v_exp_f32_e32 v108, v108
	v_exp_f32_e32 v109, v109
	v_add_f32_e32 v106, 1.0, v106
	v_add_f32_e32 v107, 1.0, v107
	v_add_f32_e32 v108, 1.0, v108
	v_add_f32_e32 v109, 1.0, v109
	v_rcp_f32_e32 v106, v106
	v_rcp_f32_e32 v107, v107
	v_rcp_f32_e32 v108, v108
	v_rcp_f32_e32 v109, v109
	v_add_f32_e32 v98, v98, v58
	v_add_f32_e32 v99, v99, v59
	v_add_f32_e32 v100, v100, v60
	v_add_f32_e32 v101, v101, v61
	v_mul_f32_e32 v98, 0xbfb8aa3b, v98
	v_mul_f32_e32 v99, 0xbfb8aa3b, v99
	v_mul_f32_e32 v100, 0xbfb8aa3b, v100
	v_mul_f32_e32 v101, 0xbfb8aa3b, v101
	v_exp_f32_e32 v98, v98
	v_exp_f32_e32 v99, v99
	v_exp_f32_e32 v100, v100
	v_exp_f32_e32 v101, v101
	v_add_f32_e32 v98, 1.0, v98
	v_add_f32_e32 v99, 1.0, v99
	v_add_f32_e32 v100, 1.0, v100
	v_add_f32_e32 v101, 1.0, v101
	v_rcp_f32_e32 v98, v98
	v_rcp_f32_e32 v99, v99
	v_rcp_f32_e32 v100, v100
	v_rcp_f32_e32 v101, v101
	v_add_f32_e32 v90, v90, v74
	v_add_f32_e32 v91, v91, v75
	v_add_f32_e32 v92, v92, v76
	v_add_f32_e32 v93, v93, v77
	v_mul_f32_e32 v90, 0xbfb8aa3b, v90
	v_mul_f32_e32 v91, 0xbfb8aa3b, v91
	v_mul_f32_e32 v92, 0xbfb8aa3b, v92
	v_mul_f32_e32 v93, 0xbfb8aa3b, v93
	s_waitcnt vmcnt(1)
	v_lshlrev_b32_e32 v129, 16, v134
	v_and_b32_e32 v130, 0xffff0000, v134
	v_lshlrev_b32_e32 v131, 16, v135
	v_and_b32_e32 v132, 0xffff0000, v135
	v_lshlrev_b32_e32 v133, 16, v136
	v_and_b32_e32 v134, 0xffff0000, v136
	v_lshlrev_b32_e32 v135, 16, v137
	v_and_b32_e32 v136, 0xffff0000, v137
	v_mul_f32_e32 v1, v1, v129
	v_mul_f32_e32 v129, v122, v133
	v_mul_f32_e32 v122, v126, v130
	v_mul_f32_e32 v126, v123, v134
	v_mul_f32_e32 v123, v127, v131
	v_mul_f32_e32 v127, v124, v135
	v_mul_f32_e32 v124, v128, v132
	v_mul_f32_e32 v125, v125, v136
	v_cvt_pk_bf16_f32 v122, v1, v122
	v_cvt_pk_bf16_f32 v123, v123, v124
	v_cvt_pk_bf16_f32 v124, v129, v126
	v_cvt_pk_bf16_f32 v125, v127, v125
	global_load_dwordx4 v[126:129], v[154:155], off offset:256
	v_add_f32_e32 v1, v118, v62
	v_add_f32_e32 v118, v119, v63
	v_add_f32_e32 v119, v120, v64
	v_add_f32_e32 v120, v121, v65
	v_mul_f32_e32 v1, 0xbfb8aa3b, v1
	v_mul_f32_e32 v118, 0xbfb8aa3b, v118
	v_mul_f32_e32 v119, 0xbfb8aa3b, v119
	v_mul_f32_e32 v120, 0xbfb8aa3b, v120
	v_exp_f32_e32 v1, v1
	v_exp_f32_e32 v118, v118
	v_exp_f32_e32 v119, v119
	v_exp_f32_e32 v120, v120
	v_add_f32_e32 v1, 1.0, v1
	v_add_f32_e32 v118, 1.0, v118
	v_add_f32_e32 v119, 1.0, v119
	v_add_f32_e32 v120, 1.0, v120
	v_add_u32_e32 v130, 32, v148
	v_lshlrev_b64 v[132:133], 11, v[150:151]
	v_rcp_f32_e32 v1, v1
	v_rcp_f32_e32 v118, v118
	v_rcp_f32_e32 v119, v119
	v_rcp_f32_e32 v120, v120
	v_ashrrev_i32_e32 v131, 31, v130
	v_lshl_add_u64 v[132:133], s[60:61], 0, v[132:133]
	v_lshlrev_b64 v[134:135], 10, v[130:131]
	v_lshl_add_u64 v[132:133], v[132:133], 0, v[146:147]
	v_lshl_add_u64 v[134:135], s[80:81], 0, v[134:135]
	global_store_dwordx4 v[132:133], v[122:125], off offset:1024
	v_lshl_add_u64 v[134:135], v[134:135], 0, v[146:147]
	v_exp_f32_e32 v90, v90
	v_exp_f32_e32 v91, v91
	v_exp_f32_e32 v92, v92
	v_exp_f32_e32 v93, v93
	v_add_f32_e32 v90, 1.0, v90
	v_add_f32_e32 v91, 1.0, v91
	v_add_f32_e32 v92, 1.0, v92
	v_add_f32_e32 v93, 1.0, v93
	v_rcp_f32_e32 v90, v90
	v_rcp_f32_e32 v91, v91
	v_rcp_f32_e32 v92, v92
	v_rcp_f32_e32 v93, v93
	v_add_f32_e32 v82, v82, v58
	v_add_f32_e32 v83, v83, v59
	v_add_f32_e32 v84, v84, v60
	v_add_f32_e32 v85, v85, v61
	v_mul_f32_e32 v82, 0xbfb8aa3b, v82
	v_mul_f32_e32 v83, 0xbfb8aa3b, v83
	v_mul_f32_e32 v84, 0xbfb8aa3b, v84
	v_mul_f32_e32 v85, 0xbfb8aa3b, v85
	v_exp_f32_e32 v82, v82
	v_exp_f32_e32 v83, v83
	v_exp_f32_e32 v84, v84
	v_exp_f32_e32 v85, v85
	v_add_f32_e32 v82, 1.0, v82
	v_add_f32_e32 v83, 1.0, v83
	v_add_f32_e32 v84, 1.0, v84
	v_add_f32_e32 v85, 1.0, v85
	v_rcp_f32_e32 v82, v82
	v_rcp_f32_e32 v83, v83
	v_rcp_f32_e32 v84, v84
	v_rcp_f32_e32 v85, v85
	v_add_f32_e32 v66, v66, v74
	v_add_f32_e32 v67, v67, v75
	v_add_f32_e32 v68, v68, v76
	v_add_f32_e32 v69, v69, v77
	v_mul_f32_e32 v66, 0xbfb8aa3b, v66
	v_mul_f32_e32 v67, 0xbfb8aa3b, v67
	v_mul_f32_e32 v68, 0xbfb8aa3b, v68
	v_mul_f32_e32 v69, 0xbfb8aa3b, v69
	v_exp_f32_e32 v66, v66
	v_exp_f32_e32 v67, v67
	v_exp_f32_e32 v68, v68
	v_exp_f32_e32 v69, v69
	v_add_f32_e32 v66, 1.0, v66
	v_add_f32_e32 v67, 1.0, v67
	v_add_f32_e32 v68, 1.0, v68
	v_add_f32_e32 v69, 1.0, v69
	v_rcp_f32_e32 v66, v66
	v_rcp_f32_e32 v67, v67
	s_waitcnt vmcnt(1)
	v_lshlrev_b32_e32 v121, 16, v126
	v_and_b32_e32 v122, 0xffff0000, v126
	v_lshlrev_b32_e32 v123, 16, v127
	v_and_b32_e32 v124, 0xffff0000, v127
	v_lshlrev_b32_e32 v125, 16, v128
	v_and_b32_e32 v126, 0xffff0000, v128
	v_lshlrev_b32_e32 v127, 16, v129
	v_and_b32_e32 v128, 0xffff0000, v129
	v_mul_f32_e32 v1, v1, v121
	v_mul_f32_e32 v121, v114, v125
	v_mul_f32_e32 v114, v118, v122
	v_mul_f32_e32 v118, v115, v126
	v_mul_f32_e32 v115, v119, v123
	v_mul_f32_e32 v119, v116, v127
	v_mul_f32_e32 v116, v120, v124
	v_mul_f32_e32 v117, v117, v128
	v_cvt_pk_bf16_f32 v114, v1, v114
	v_cvt_pk_bf16_f32 v115, v115, v116
	v_cvt_pk_bf16_f32 v116, v121, v118
	v_cvt_pk_bf16_f32 v117, v119, v117
	global_load_dwordx4 v[118:121], v[134:135], off
	v_add_f32_e32 v1, v110, v78
	v_add_f32_e32 v110, v111, v79
	v_add_f32_e32 v111, v112, v80
	v_add_f32_e32 v112, v113, v81
	v_mul_f32_e32 v1, 0xbfb8aa3b, v1
	v_mul_f32_e32 v110, 0xbfb8aa3b, v110
	v_mul_f32_e32 v111, 0xbfb8aa3b, v111
	v_mul_f32_e32 v112, 0xbfb8aa3b, v112
	v_exp_f32_e32 v1, v1
	v_exp_f32_e32 v110, v110
	v_exp_f32_e32 v111, v111
	v_exp_f32_e32 v112, v112
	v_add_f32_e32 v1, 1.0, v1
	v_add_f32_e32 v110, 1.0, v110
	v_add_f32_e32 v111, 1.0, v111
	v_add_f32_e32 v112, 1.0, v112
	v_rcp_f32_e32 v1, v1
	v_rcp_f32_e32 v110, v110
	v_rcp_f32_e32 v111, v111
	v_rcp_f32_e32 v112, v112
	global_store_dwordx4 v[132:133], v[114:117], off offset:1280
	v_rcp_f32_e32 v68, v68
	v_rcp_f32_e32 v69, v69
	v_add_f32_e32 v50, v50, v58
	v_add_f32_e32 v51, v51, v59
	v_add_f32_e32 v52, v52, v60
	v_add_f32_e32 v53, v53, v61
	v_mul_f32_e32 v50, 0xbfb8aa3b, v50
	v_mul_f32_e32 v51, 0xbfb8aa3b, v51
	v_mul_f32_e32 v52, 0xbfb8aa3b, v52
	v_mul_f32_e32 v53, 0xbfb8aa3b, v53
	v_exp_f32_e32 v50, v50
	v_exp_f32_e32 v51, v51
	v_exp_f32_e32 v52, v52
	v_exp_f32_e32 v53, v53
	v_add_f32_e32 v50, 1.0, v50
	v_add_f32_e32 v51, 1.0, v51
	v_add_f32_e32 v52, 1.0, v52
	v_add_f32_e32 v53, 1.0, v53
	v_rcp_f32_e32 v50, v50
	v_rcp_f32_e32 v51, v51
	v_rcp_f32_e32 v52, v52
	v_rcp_f32_e32 v53, v53
	v_add_f32_e32 v42, v42, v74
	v_add_f32_e32 v43, v43, v75
	v_add_f32_e32 v44, v44, v76
	v_add_f32_e32 v45, v45, v77
	v_mul_f32_e32 v42, 0xbfb8aa3b, v42
	v_mul_f32_e32 v43, 0xbfb8aa3b, v43
	v_mul_f32_e32 v44, 0xbfb8aa3b, v44
	v_mul_f32_e32 v45, 0xbfb8aa3b, v45
	v_exp_f32_e32 v42, v42
	v_exp_f32_e32 v43, v43
	v_exp_f32_e32 v44, v44
	v_exp_f32_e32 v45, v45
	v_add_f32_e32 v42, 1.0, v42
	v_add_f32_e32 v43, 1.0, v43
	v_add_f32_e32 v44, 1.0, v44
	v_add_f32_e32 v45, 1.0, v45
	v_rcp_f32_e32 v42, v42
	v_rcp_f32_e32 v43, v43
	v_rcp_f32_e32 v44, v44
	v_rcp_f32_e32 v45, v45
	v_add_f32_e32 v34, v34, v58
	v_add_f32_e32 v35, v35, v59
	v_add_f32_e32 v36, v36, v60
	v_add_f32_e32 v37, v37, v61
	v_mul_f32_e32 v34, 0xbfb8aa3b, v34
	v_mul_f32_e32 v35, 0xbfb8aa3b, v35
	v_mul_f32_e32 v36, 0xbfb8aa3b, v36
	v_mul_f32_e32 v37, 0xbfb8aa3b, v37
	v_exp_f32_e32 v34, v34
	v_exp_f32_e32 v35, v35
	v_exp_f32_e32 v36, v36
	v_exp_f32_e32 v37, v37
	v_add_f32_e32 v34, 1.0, v34
	v_add_f32_e32 v35, 1.0, v35
	v_add_f32_e32 v36, 1.0, v36
	v_add_f32_e32 v37, 1.0, v37
	s_waitcnt vmcnt(1)
	v_lshlrev_b32_e32 v113, 16, v118
	v_and_b32_e32 v114, 0xffff0000, v118
	v_lshlrev_b32_e32 v115, 16, v119
	v_and_b32_e32 v116, 0xffff0000, v119
	v_lshlrev_b32_e32 v117, 16, v120
	v_and_b32_e32 v118, 0xffff0000, v120
	v_lshlrev_b32_e32 v119, 16, v121
	v_and_b32_e32 v120, 0xffff0000, v121
	v_mul_f32_e32 v1, v1, v113
	v_mul_f32_e32 v113, v106, v117
	v_mul_f32_e32 v106, v110, v114
	v_mul_f32_e32 v110, v107, v118
	v_mul_f32_e32 v107, v111, v115
	v_mul_f32_e32 v111, v108, v119
	v_mul_f32_e32 v108, v112, v116
	v_mul_f32_e32 v109, v109, v120
	v_cvt_pk_bf16_f32 v106, v1, v106
	v_cvt_pk_bf16_f32 v107, v107, v108
	v_cvt_pk_bf16_f32 v108, v113, v110
	v_cvt_pk_bf16_f32 v109, v111, v109
	global_load_dwordx4 v[110:113], v[134:135], off offset:256
	v_add_f32_e32 v1, v102, v62
	v_add_f32_e32 v102, v103, v63
	v_add_f32_e32 v103, v104, v64
	v_add_f32_e32 v104, v105, v65
	v_mul_f32_e32 v1, 0xbfb8aa3b, v1
	v_mul_f32_e32 v102, 0xbfb8aa3b, v102
	v_mul_f32_e32 v103, 0xbfb8aa3b, v103
	v_mul_f32_e32 v104, 0xbfb8aa3b, v104
	v_exp_f32_e32 v1, v1
	v_exp_f32_e32 v102, v102
	v_exp_f32_e32 v103, v103
	v_exp_f32_e32 v104, v104
	v_add_f32_e32 v1, 1.0, v1
	v_add_f32_e32 v102, 1.0, v102
	v_add_f32_e32 v103, 1.0, v103
	v_add_f32_e32 v104, 1.0, v104
	v_add_u32_e32 v114, 0xffff15a0, v148
	v_lshlrev_b64 v[116:117], 11, v[130:131]
	v_rcp_f32_e32 v1, v1
	v_rcp_f32_e32 v102, v102
	v_rcp_f32_e32 v103, v103
	v_rcp_f32_e32 v104, v104
	v_ashrrev_i32_e32 v115, 31, v114
	v_lshl_add_u64 v[116:117], s[60:61], 0, v[116:117]
	v_lshlrev_b64 v[118:119], 10, v[114:115]
	v_lshl_add_u64 v[116:117], v[116:117], 0, v[146:147]
	v_lshl_add_u64 v[118:119], s[80:81], 0, v[118:119]
	global_store_dwordx4 v[116:117], v[106:109], off offset:1024
	v_lshl_add_u64 v[118:119], v[118:119], 0, v[146:147]
	v_rcp_f32_e32 v34, v34
	v_rcp_f32_e32 v35, v35
	v_rcp_f32_e32 v36, v36
	v_rcp_f32_e32 v37, v37
	v_add_f32_e32 v26, v26, v74
	v_add_f32_e32 v27, v27, v75
	v_add_f32_e32 v28, v28, v76
	v_add_f32_e32 v29, v29, v77
	v_mul_f32_e32 v26, 0xbfb8aa3b, v26
	v_mul_f32_e32 v27, 0xbfb8aa3b, v27
	v_mul_f32_e32 v28, 0xbfb8aa3b, v28
	v_mul_f32_e32 v29, 0xbfb8aa3b, v29
	v_exp_f32_e32 v26, v26
	v_exp_f32_e32 v27, v27
	v_exp_f32_e32 v28, v28
	v_exp_f32_e32 v29, v29
	v_add_f32_e32 v26, 1.0, v26
	v_add_f32_e32 v27, 1.0, v27
	v_add_f32_e32 v28, 1.0, v28
	v_add_f32_e32 v29, 1.0, v29
	v_rcp_f32_e32 v26, v26
	v_rcp_f32_e32 v27, v27
	v_rcp_f32_e32 v28, v28
	v_rcp_f32_e32 v29, v29
	v_add_f32_e32 v18, v18, v58
	v_add_f32_e32 v19, v19, v59
	v_add_f32_e32 v20, v20, v60
	v_add_f32_e32 v21, v21, v61
	v_mul_f32_e32 v18, 0xbfb8aa3b, v18
	v_mul_f32_e32 v19, 0xbfb8aa3b, v19
	v_mul_f32_e32 v20, 0xbfb8aa3b, v20
	v_mul_f32_e32 v21, 0xbfb8aa3b, v21
	v_exp_f32_e32 v18, v18
	v_exp_f32_e32 v19, v19
	v_exp_f32_e32 v20, v20
	v_exp_f32_e32 v21, v21
	v_add_f32_e32 v18, 1.0, v18
	v_add_f32_e32 v19, 1.0, v19
	v_add_f32_e32 v20, 1.0, v20
	v_add_f32_e32 v21, 1.0, v21
	v_rcp_f32_e32 v18, v18
	v_rcp_f32_e32 v19, v19
	v_rcp_f32_e32 v20, v20
	v_rcp_f32_e32 v21, v21
	v_add_f32_e32 v10, v10, v74
	v_add_f32_e32 v11, v11, v75
	v_add_f32_e32 v12, v12, v76
	v_add_f32_e32 v13, v13, v77
	v_mul_f32_e32 v10, 0xbfb8aa3b, v10
	v_mul_f32_e32 v11, 0xbfb8aa3b, v11
	s_waitcnt vmcnt(1)
	v_lshlrev_b32_e32 v105, 16, v110
	v_and_b32_e32 v106, 0xffff0000, v110
	v_lshlrev_b32_e32 v107, 16, v111
	v_and_b32_e32 v108, 0xffff0000, v111
	v_lshlrev_b32_e32 v109, 16, v112
	v_and_b32_e32 v110, 0xffff0000, v112
	v_lshlrev_b32_e32 v111, 16, v113
	v_and_b32_e32 v112, 0xffff0000, v113
	v_mul_f32_e32 v1, v1, v105
	v_mul_f32_e32 v105, v98, v109
	v_mul_f32_e32 v98, v102, v106
	v_mul_f32_e32 v102, v99, v110
	v_mul_f32_e32 v99, v103, v107
	v_mul_f32_e32 v103, v100, v111
	v_mul_f32_e32 v100, v104, v108
	v_mul_f32_e32 v101, v101, v112
	v_cvt_pk_bf16_f32 v98, v1, v98
	v_cvt_pk_bf16_f32 v99, v99, v100
	v_cvt_pk_bf16_f32 v100, v105, v102
	v_cvt_pk_bf16_f32 v101, v103, v101
	global_load_dwordx4 v[102:105], v[118:119], off
	v_add_f32_e32 v1, v94, v78
	v_add_f32_e32 v94, v95, v79
	v_add_f32_e32 v95, v96, v80
	v_add_f32_e32 v96, v97, v81
	v_mul_f32_e32 v1, 0xbfb8aa3b, v1
	v_mul_f32_e32 v94, 0xbfb8aa3b, v94
	v_mul_f32_e32 v95, 0xbfb8aa3b, v95
	v_mul_f32_e32 v96, 0xbfb8aa3b, v96
	v_exp_f32_e32 v1, v1
	v_exp_f32_e32 v94, v94
	v_exp_f32_e32 v95, v95
	v_exp_f32_e32 v96, v96
	v_add_f32_e32 v1, 1.0, v1
	v_add_f32_e32 v94, 1.0, v94
	v_add_f32_e32 v95, 1.0, v95
	v_add_f32_e32 v96, 1.0, v96
	v_rcp_f32_e32 v1, v1
	v_rcp_f32_e32 v94, v94
	v_rcp_f32_e32 v95, v95
	v_rcp_f32_e32 v96, v96
	global_store_dwordx4 v[116:117], v[98:101], off offset:1280
	v_mul_f32_e32 v12, 0xbfb8aa3b, v12
	v_mul_f32_e32 v13, 0xbfb8aa3b, v13
	v_exp_f32_e32 v10, v10
	v_exp_f32_e32 v11, v11
	v_exp_f32_e32 v12, v12
	v_exp_f32_e32 v13, v13
	v_add_f32_e32 v10, 1.0, v10
	v_add_f32_e32 v11, 1.0, v11
	v_add_f32_e32 v12, 1.0, v12
	v_add_f32_e32 v13, 1.0, v13
	v_rcp_f32_e32 v10, v10
	v_rcp_f32_e32 v11, v11
	v_rcp_f32_e32 v12, v12
	v_rcp_f32_e32 v13, v13
	v_add_f32_e32 v2, v2, v58
	v_add_f32_e32 v3, v3, v59
	v_add_f32_e32 v4, v4, v60
	v_add_f32_e32 v5, v5, v61
	v_mul_f32_e32 v2, 0xbfb8aa3b, v2
	v_mul_f32_e32 v3, 0xbfb8aa3b, v3
	v_mul_f32_e32 v4, 0xbfb8aa3b, v4
	v_mul_f32_e32 v5, 0xbfb8aa3b, v5
	v_exp_f32_e32 v2, v2
	v_exp_f32_e32 v3, v3
	v_exp_f32_e32 v4, v4
	v_exp_f32_e32 v5, v5
	v_add_f32_e32 v2, 1.0, v2
	v_add_f32_e32 v3, 1.0, v3
	v_add_f32_e32 v4, 1.0, v4
	v_add_f32_e32 v5, 1.0, v5
	v_rcp_f32_e32 v2, v2
	v_rcp_f32_e32 v3, v3
	v_rcp_f32_e32 v4, v4
	v_rcp_f32_e32 v5, v5
	s_waitcnt vmcnt(1)
	v_lshlrev_b32_e32 v97, 16, v102
	v_and_b32_e32 v98, 0xffff0000, v102
	v_lshlrev_b32_e32 v99, 16, v103
	v_and_b32_e32 v100, 0xffff0000, v103
	v_lshlrev_b32_e32 v101, 16, v104
	v_and_b32_e32 v102, 0xffff0000, v104
	v_lshlrev_b32_e32 v103, 16, v105
	v_and_b32_e32 v104, 0xffff0000, v105
	v_mul_f32_e32 v1, v1, v97
	v_mul_f32_e32 v97, v90, v101
	v_mul_f32_e32 v90, v94, v98
	v_mul_f32_e32 v94, v91, v102
	v_mul_f32_e32 v91, v95, v99
	v_mul_f32_e32 v95, v92, v103
	v_mul_f32_e32 v92, v96, v100
	v_mul_f32_e32 v93, v93, v104
	v_cvt_pk_bf16_f32 v90, v1, v90
	v_cvt_pk_bf16_f32 v91, v91, v92
	v_cvt_pk_bf16_f32 v92, v97, v94
	v_cvt_pk_bf16_f32 v93, v95, v93
	global_load_dwordx4 v[94:97], v[118:119], off offset:256
	v_add_f32_e32 v1, v86, v62
	v_add_f32_e32 v86, v87, v63
	v_add_f32_e32 v87, v88, v64
	v_add_f32_e32 v88, v89, v65
	v_mul_f32_e32 v1, 0xbfb8aa3b, v1
	v_mul_f32_e32 v86, 0xbfb8aa3b, v86
	v_mul_f32_e32 v87, 0xbfb8aa3b, v87
	v_mul_f32_e32 v88, 0xbfb8aa3b, v88
	v_exp_f32_e32 v1, v1
	v_exp_f32_e32 v86, v86
	v_exp_f32_e32 v87, v87
	v_exp_f32_e32 v88, v88
	v_add_f32_e32 v1, 1.0, v1
	v_add_f32_e32 v86, 1.0, v86
	v_add_f32_e32 v87, 1.0, v87
	v_add_f32_e32 v88, 1.0, v88
	v_add_u32_e32 v98, 0x60, v148
	v_lshlrev_b64 v[100:101], 11, v[114:115]
	v_rcp_f32_e32 v1, v1
	v_rcp_f32_e32 v86, v86
	v_rcp_f32_e32 v87, v87
	v_rcp_f32_e32 v88, v88
	v_ashrrev_i32_e32 v99, 31, v98
	v_lshl_add_u64 v[100:101], s[60:61], 0, v[100:101]
	v_lshlrev_b64 v[102:103], 10, v[98:99]
	v_lshl_add_u64 v[100:101], v[100:101], 0, v[146:147]
	v_lshl_add_u64 v[102:103], s[80:81], 0, v[102:103]
	global_store_dwordx4 v[100:101], v[90:93], off offset:1024
	v_lshl_add_u64 v[102:103], v[102:103], 0, v[146:147]
	s_waitcnt vmcnt(1)
	v_lshlrev_b32_e32 v89, 16, v94
	v_and_b32_e32 v90, 0xffff0000, v94
	v_lshlrev_b32_e32 v91, 16, v95
	v_and_b32_e32 v92, 0xffff0000, v95
	v_lshlrev_b32_e32 v93, 16, v96
	v_and_b32_e32 v94, 0xffff0000, v96
	v_lshlrev_b32_e32 v95, 16, v97
	v_and_b32_e32 v96, 0xffff0000, v97
	v_mul_f32_e32 v1, v1, v89
	v_mul_f32_e32 v89, v82, v93
	v_mul_f32_e32 v82, v86, v90
	v_mul_f32_e32 v86, v83, v94
	v_mul_f32_e32 v83, v87, v91
	v_mul_f32_e32 v87, v84, v95
	v_mul_f32_e32 v84, v88, v92
	v_mul_f32_e32 v85, v85, v96
	v_cvt_pk_bf16_f32 v82, v1, v82
	v_cvt_pk_bf16_f32 v83, v83, v84
	v_cvt_pk_bf16_f32 v84, v89, v86
	v_cvt_pk_bf16_f32 v85, v87, v85
	global_load_dwordx4 v[86:89], v[102:103], off
	v_add_f32_e32 v1, v70, v78
	v_add_f32_e32 v70, v71, v79
	v_add_f32_e32 v71, v72, v80
	v_add_f32_e32 v72, v73, v81
	v_mul_f32_e32 v1, 0xbfb8aa3b, v1
	v_mul_f32_e32 v70, 0xbfb8aa3b, v70
	v_mul_f32_e32 v71, 0xbfb8aa3b, v71
	v_mul_f32_e32 v72, 0xbfb8aa3b, v72
	v_exp_f32_e32 v1, v1
	v_exp_f32_e32 v70, v70
	v_exp_f32_e32 v71, v71
	v_exp_f32_e32 v72, v72
	v_add_f32_e32 v1, 1.0, v1
	v_add_f32_e32 v70, 1.0, v70
	v_add_f32_e32 v71, 1.0, v71
	v_add_f32_e32 v72, 1.0, v72
	v_rcp_f32_e32 v1, v1
	v_rcp_f32_e32 v70, v70
	v_rcp_f32_e32 v71, v71
	v_rcp_f32_e32 v72, v72
	global_store_dwordx4 v[100:101], v[82:85], off offset:1280
	s_waitcnt vmcnt(1)
	v_lshlrev_b32_e32 v73, 16, v86
	v_and_b32_e32 v82, 0xffff0000, v86
	v_lshlrev_b32_e32 v83, 16, v87
	v_and_b32_e32 v84, 0xffff0000, v87
	v_lshlrev_b32_e32 v85, 16, v88
	v_and_b32_e32 v86, 0xffff0000, v88
	v_lshlrev_b32_e32 v87, 16, v89
	v_and_b32_e32 v88, 0xffff0000, v89
	v_mul_f32_e32 v1, v1, v73
	v_mul_f32_e32 v73, v66, v85
	v_mul_f32_e32 v66, v70, v82
	v_mul_f32_e32 v70, v67, v86
	v_mul_f32_e32 v67, v71, v83
	v_mul_f32_e32 v71, v68, v87
	v_mul_f32_e32 v68, v72, v84
	v_mul_f32_e32 v69, v69, v88
	v_cvt_pk_bf16_f32 v66, v1, v66
	v_cvt_pk_bf16_f32 v67, v67, v68
	v_cvt_pk_bf16_f32 v68, v73, v70
	v_cvt_pk_bf16_f32 v69, v71, v69
	global_load_dwordx4 v[70:73], v[102:103], off offset:256
	v_add_f32_e32 v1, v54, v62
	v_add_f32_e32 v54, v55, v63
	v_add_f32_e32 v55, v56, v64
	v_add_f32_e32 v56, v57, v65
	v_mul_f32_e32 v1, 0xbfb8aa3b, v1
	v_mul_f32_e32 v54, 0xbfb8aa3b, v54
	v_mul_f32_e32 v55, 0xbfb8aa3b, v55
	v_mul_f32_e32 v56, 0xbfb8aa3b, v56
	v_exp_f32_e32 v1, v1
	v_exp_f32_e32 v54, v54
	v_exp_f32_e32 v55, v55
	v_exp_f32_e32 v56, v56
	v_add_f32_e32 v1, 1.0, v1
	v_add_f32_e32 v54, 1.0, v54
	v_add_f32_e32 v55, 1.0, v55
	v_add_f32_e32 v56, 1.0, v56
	v_add_u32_e32 v82, 0x70, v148
	v_lshlrev_b64 v[84:85], 11, v[98:99]
	v_rcp_f32_e32 v1, v1
	v_rcp_f32_e32 v54, v54
	v_rcp_f32_e32 v55, v55
	v_rcp_f32_e32 v56, v56
	v_ashrrev_i32_e32 v83, 31, v82
	v_lshl_add_u64 v[84:85], s[60:61], 0, v[84:85]
	v_lshlrev_b64 v[86:87], 10, v[82:83]
	v_lshl_add_u64 v[84:85], v[84:85], 0, v[146:147]
	v_lshl_add_u64 v[86:87], s[80:81], 0, v[86:87]
	global_store_dwordx4 v[84:85], v[66:69], off offset:1024
	v_lshl_add_u64 v[86:87], v[86:87], 0, v[146:147]
	s_waitcnt vmcnt(1)
	v_lshlrev_b32_e32 v57, 16, v70
	v_and_b32_e32 v66, 0xffff0000, v70
	v_lshlrev_b32_e32 v67, 16, v71
	v_and_b32_e32 v68, 0xffff0000, v71
	v_lshlrev_b32_e32 v69, 16, v72
	v_and_b32_e32 v70, 0xffff0000, v72
	v_lshlrev_b32_e32 v71, 16, v73
	v_and_b32_e32 v72, 0xffff0000, v73
	v_mul_f32_e32 v1, v1, v57
	v_mul_f32_e32 v57, v50, v69
	v_mul_f32_e32 v50, v54, v66
	v_mul_f32_e32 v54, v51, v70
	v_mul_f32_e32 v51, v55, v67
	v_mul_f32_e32 v55, v52, v71
	v_mul_f32_e32 v52, v56, v68
	v_mul_f32_e32 v53, v53, v72
	v_cvt_pk_bf16_f32 v50, v1, v50
	v_cvt_pk_bf16_f32 v51, v51, v52
	v_cvt_pk_bf16_f32 v52, v57, v54
	v_cvt_pk_bf16_f32 v53, v55, v53
	global_load_dwordx4 v[54:57], v[86:87], off
	v_add_f32_e32 v1, v46, v78
	v_add_f32_e32 v46, v47, v79
	v_add_f32_e32 v47, v48, v80
	v_add_f32_e32 v48, v49, v81
	v_mul_f32_e32 v1, 0xbfb8aa3b, v1
	v_mul_f32_e32 v46, 0xbfb8aa3b, v46
	v_mul_f32_e32 v47, 0xbfb8aa3b, v47
	v_mul_f32_e32 v48, 0xbfb8aa3b, v48
	v_exp_f32_e32 v1, v1
	v_exp_f32_e32 v46, v46
	v_exp_f32_e32 v47, v47
	v_exp_f32_e32 v48, v48
	v_add_f32_e32 v1, 1.0, v1
	v_add_f32_e32 v46, 1.0, v46
	v_add_f32_e32 v47, 1.0, v47
	v_add_f32_e32 v48, 1.0, v48
	v_rcp_f32_e32 v1, v1
	v_rcp_f32_e32 v46, v46
	v_rcp_f32_e32 v47, v47
	v_rcp_f32_e32 v48, v48
	global_store_dwordx4 v[84:85], v[50:53], off offset:1280
	s_waitcnt vmcnt(1)
	v_lshlrev_b32_e32 v49, 16, v54
	v_and_b32_e32 v50, 0xffff0000, v54
	v_lshlrev_b32_e32 v51, 16, v55
	v_and_b32_e32 v52, 0xffff0000, v55
	v_lshlrev_b32_e32 v53, 16, v56
	v_and_b32_e32 v54, 0xffff0000, v56
	v_lshlrev_b32_e32 v55, 16, v57
	v_and_b32_e32 v56, 0xffff0000, v57
	v_mul_f32_e32 v1, v1, v49
	v_mul_f32_e32 v49, v42, v53
	v_mul_f32_e32 v42, v46, v50
	v_mul_f32_e32 v46, v43, v54
	v_mul_f32_e32 v43, v47, v51
	v_mul_f32_e32 v47, v44, v55
	v_mul_f32_e32 v44, v48, v52
	v_mul_f32_e32 v45, v45, v56
	v_cvt_pk_bf16_f32 v42, v1, v42
	v_cvt_pk_bf16_f32 v43, v43, v44
	v_cvt_pk_bf16_f32 v44, v49, v46
	v_cvt_pk_bf16_f32 v45, v47, v45
	global_load_dwordx4 v[46:49], v[86:87], off offset:256
	v_add_f32_e32 v1, v38, v62
	v_add_f32_e32 v38, v39, v63
	v_add_f32_e32 v39, v40, v64
	v_add_f32_e32 v40, v41, v65
	v_mul_f32_e32 v1, 0xbfb8aa3b, v1
	v_mul_f32_e32 v38, 0xbfb8aa3b, v38
	v_mul_f32_e32 v39, 0xbfb8aa3b, v39
	v_mul_f32_e32 v40, 0xbfb8aa3b, v40
	v_exp_f32_e32 v1, v1
	v_exp_f32_e32 v38, v38
	v_exp_f32_e32 v39, v39
	v_exp_f32_e32 v40, v40
	v_add_f32_e32 v1, 1.0, v1
	v_add_f32_e32 v38, 1.0, v38
	v_add_f32_e32 v39, 1.0, v39
	v_add_f32_e32 v40, 1.0, v40
	v_add_u32_e32 v50, 0x80, v148
	v_lshlrev_b64 v[52:53], 11, v[82:83]
	v_rcp_f32_e32 v1, v1
	v_rcp_f32_e32 v38, v38
	v_rcp_f32_e32 v39, v39
	v_rcp_f32_e32 v40, v40
	v_ashrrev_i32_e32 v51, 31, v50
	v_lshl_add_u64 v[52:53], s[60:61], 0, v[52:53]
	v_lshlrev_b64 v[54:55], 10, v[50:51]
	v_lshl_add_u64 v[52:53], v[52:53], 0, v[146:147]
	v_lshl_add_u64 v[54:55], s[80:81], 0, v[54:55]
	global_store_dwordx4 v[52:53], v[42:45], off offset:1024
	v_lshl_add_u64 v[54:55], v[54:55], 0, v[146:147]
	s_waitcnt vmcnt(1)
	v_lshlrev_b32_e32 v41, 16, v46
	v_and_b32_e32 v42, 0xffff0000, v46
	v_lshlrev_b32_e32 v43, 16, v47
	v_and_b32_e32 v44, 0xffff0000, v47
	v_lshlrev_b32_e32 v45, 16, v48
	v_and_b32_e32 v46, 0xffff0000, v48
	v_lshlrev_b32_e32 v47, 16, v49
	v_and_b32_e32 v48, 0xffff0000, v49
	v_mul_f32_e32 v1, v1, v41
	v_mul_f32_e32 v41, v34, v45
	v_mul_f32_e32 v34, v38, v42
	v_mul_f32_e32 v38, v35, v46
	v_mul_f32_e32 v35, v39, v43
	v_mul_f32_e32 v39, v36, v47
	v_mul_f32_e32 v36, v40, v44
	v_mul_f32_e32 v37, v37, v48
	v_cvt_pk_bf16_f32 v34, v1, v34
	v_cvt_pk_bf16_f32 v35, v35, v36
	v_cvt_pk_bf16_f32 v36, v41, v38
	v_cvt_pk_bf16_f32 v37, v39, v37
	global_load_dwordx4 v[38:41], v[54:55], off
	v_add_f32_e32 v1, v30, v78
	v_add_f32_e32 v30, v31, v79
	v_add_f32_e32 v31, v32, v80
	v_add_f32_e32 v32, v33, v81
	v_mul_f32_e32 v1, 0xbfb8aa3b, v1
	v_mul_f32_e32 v30, 0xbfb8aa3b, v30
	v_mul_f32_e32 v31, 0xbfb8aa3b, v31
	v_mul_f32_e32 v32, 0xbfb8aa3b, v32
	v_exp_f32_e32 v1, v1
	v_exp_f32_e32 v30, v30
	v_exp_f32_e32 v31, v31
	v_exp_f32_e32 v32, v32
	v_add_f32_e32 v1, 1.0, v1
	v_add_f32_e32 v30, 1.0, v30
	v_add_f32_e32 v31, 1.0, v31
	v_add_f32_e32 v32, 1.0, v32
	v_rcp_f32_e32 v1, v1
	v_rcp_f32_e32 v30, v30
	v_rcp_f32_e32 v31, v31
	v_rcp_f32_e32 v32, v32
	global_store_dwordx4 v[52:53], v[34:37], off offset:1280
	s_waitcnt vmcnt(1)
	v_lshlrev_b32_e32 v33, 16, v38
	v_and_b32_e32 v34, 0xffff0000, v38
	v_lshlrev_b32_e32 v35, 16, v39
	v_and_b32_e32 v36, 0xffff0000, v39
	v_lshlrev_b32_e32 v37, 16, v40
	v_and_b32_e32 v38, 0xffff0000, v40
	v_lshlrev_b32_e32 v39, 16, v41
	v_and_b32_e32 v40, 0xffff0000, v41
	v_mul_f32_e32 v1, v1, v33
	v_mul_f32_e32 v33, v26, v37
	v_mul_f32_e32 v26, v30, v34
	v_mul_f32_e32 v30, v27, v38
	v_mul_f32_e32 v27, v31, v35
	v_mul_f32_e32 v31, v28, v39
	v_mul_f32_e32 v28, v32, v36
	v_mul_f32_e32 v29, v29, v40
	v_cvt_pk_bf16_f32 v26, v1, v26
	v_cvt_pk_bf16_f32 v27, v27, v28
	v_cvt_pk_bf16_f32 v28, v33, v30
	v_cvt_pk_bf16_f32 v29, v31, v29
	global_load_dwordx4 v[30:33], v[54:55], off offset:256
	v_add_f32_e32 v1, v22, v62
	v_add_f32_e32 v22, v23, v63
	v_add_f32_e32 v23, v24, v64
	v_add_f32_e32 v24, v25, v65
	v_mul_f32_e32 v1, 0xbfb8aa3b, v1
	v_mul_f32_e32 v22, 0xbfb8aa3b, v22
	v_mul_f32_e32 v23, 0xbfb8aa3b, v23
	v_mul_f32_e32 v24, 0xbfb8aa3b, v24
	v_exp_f32_e32 v1, v1
	v_exp_f32_e32 v22, v22
	v_exp_f32_e32 v23, v23
	v_exp_f32_e32 v24, v24
	v_add_f32_e32 v1, 1.0, v1
	v_add_f32_e32 v22, 1.0, v22
	v_add_f32_e32 v23, 1.0, v23
	v_add_f32_e32 v24, 1.0, v24
	v_add_u32_e32 v34, 0xffff15a0, v148
	v_lshlrev_b64 v[36:37], 11, v[50:51]
	v_rcp_f32_e32 v1, v1
	v_rcp_f32_e32 v22, v22
	v_rcp_f32_e32 v23, v23
	v_rcp_f32_e32 v24, v24
	v_ashrrev_i32_e32 v35, 31, v34
	v_lshl_add_u64 v[36:37], s[60:61], 0, v[36:37]
	v_lshlrev_b64 v[38:39], 10, v[34:35]
	v_lshl_add_u64 v[36:37], v[36:37], 0, v[146:147]
	v_lshl_add_u64 v[38:39], s[80:81], 0, v[38:39]
	global_store_dwordx4 v[36:37], v[26:29], off offset:1024
	v_lshl_add_u64 v[38:39], v[38:39], 0, v[146:147]
	s_waitcnt vmcnt(1)
	v_lshlrev_b32_e32 v25, 16, v30
	v_and_b32_e32 v26, 0xffff0000, v30
	v_lshlrev_b32_e32 v27, 16, v31
	v_and_b32_e32 v28, 0xffff0000, v31
	v_lshlrev_b32_e32 v29, 16, v32
	v_and_b32_e32 v30, 0xffff0000, v32
	v_lshlrev_b32_e32 v31, 16, v33
	v_and_b32_e32 v32, 0xffff0000, v33
	v_mul_f32_e32 v1, v1, v25
	v_mul_f32_e32 v25, v18, v29
	v_mul_f32_e32 v18, v22, v26
	v_mul_f32_e32 v22, v19, v30
	v_mul_f32_e32 v19, v23, v27
	v_mul_f32_e32 v23, v20, v31
	v_mul_f32_e32 v20, v24, v28
	v_mul_f32_e32 v21, v21, v32
	v_cvt_pk_bf16_f32 v18, v1, v18
	v_cvt_pk_bf16_f32 v19, v19, v20
	v_cvt_pk_bf16_f32 v20, v25, v22
	v_cvt_pk_bf16_f32 v21, v23, v21
	global_load_dwordx4 v[22:25], v[38:39], off
	v_add_f32_e32 v1, v14, v78
	v_add_f32_e32 v14, v15, v79
	v_add_f32_e32 v15, v16, v80
	v_add_f32_e32 v16, v17, v81
	v_mul_f32_e32 v1, 0xbfb8aa3b, v1
	v_mul_f32_e32 v14, 0xbfb8aa3b, v14
	v_mul_f32_e32 v15, 0xbfb8aa3b, v15
	v_mul_f32_e32 v16, 0xbfb8aa3b, v16
	v_exp_f32_e32 v1, v1
	v_exp_f32_e32 v14, v14
	v_exp_f32_e32 v15, v15
	v_exp_f32_e32 v16, v16
	v_add_f32_e32 v1, 1.0, v1
	v_add_f32_e32 v14, 1.0, v14
	v_add_f32_e32 v15, 1.0, v15
	v_add_f32_e32 v16, 1.0, v16
	v_rcp_f32_e32 v1, v1
	v_rcp_f32_e32 v14, v14
	v_rcp_f32_e32 v15, v15
	v_rcp_f32_e32 v16, v16
	global_store_dwordx4 v[36:37], v[18:21], off offset:1280
	s_waitcnt vmcnt(1)
	v_lshlrev_b32_e32 v17, 16, v22
	v_and_b32_e32 v18, 0xffff0000, v22
	v_lshlrev_b32_e32 v19, 16, v23
	v_and_b32_e32 v20, 0xffff0000, v23
	v_lshlrev_b32_e32 v21, 16, v24
	v_and_b32_e32 v22, 0xffff0000, v24
	v_lshlrev_b32_e32 v23, 16, v25
	v_and_b32_e32 v24, 0xffff0000, v25
	v_mul_f32_e32 v1, v1, v17
	v_mul_f32_e32 v17, v10, v21
	v_mul_f32_e32 v10, v14, v18
	v_mul_f32_e32 v14, v11, v22
	v_mul_f32_e32 v11, v15, v19
	v_mul_f32_e32 v15, v12, v23
	v_mul_f32_e32 v12, v16, v20
	v_mul_f32_e32 v13, v13, v24
	v_cvt_pk_bf16_f32 v10, v1, v10
	v_cvt_pk_bf16_f32 v11, v11, v12
	v_cvt_pk_bf16_f32 v12, v17, v14
	v_cvt_pk_bf16_f32 v13, v15, v13
	global_load_dwordx4 v[14:17], v[38:39], off offset:256
	v_add_f32_e32 v1, v6, v62
	v_add_f32_e32 v6, v7, v63
	v_add_f32_e32 v7, v8, v64
	v_add_f32_e32 v8, v9, v65
	v_mul_f32_e32 v1, 0xbfb8aa3b, v1
	v_mul_f32_e32 v6, 0xbfb8aa3b, v6
	v_mul_f32_e32 v7, 0xbfb8aa3b, v7
	v_mul_f32_e32 v8, 0xbfb8aa3b, v8
	v_exp_f32_e32 v1, v1
	v_exp_f32_e32 v6, v6
	v_exp_f32_e32 v7, v7
	v_exp_f32_e32 v8, v8
	v_add_f32_e32 v1, 1.0, v1
	v_add_f32_e32 v6, 1.0, v6
	v_add_f32_e32 v7, 1.0, v7
	v_add_f32_e32 v8, 1.0, v8
	v_lshlrev_b64 v[18:19], 11, v[34:35]
	v_rcp_f32_e32 v1, v1
	v_rcp_f32_e32 v6, v6
	v_rcp_f32_e32 v7, v7
	v_rcp_f32_e32 v8, v8
	v_lshl_add_u64 v[18:19], s[60:61], 0, v[18:19]
	v_lshl_add_u64 v[18:19], v[18:19], 0, v[146:147]
	global_store_dwordx4 v[18:19], v[10:13], off offset:1024
	s_waitcnt vmcnt(1)
	v_lshlrev_b32_e32 v9, 16, v14
	v_and_b32_e32 v10, 0xffff0000, v14
	v_lshlrev_b32_e32 v11, 16, v15
	v_and_b32_e32 v12, 0xffff0000, v15
	v_lshlrev_b32_e32 v13, 16, v16
	v_and_b32_e32 v14, 0xffff0000, v16
	v_lshlrev_b32_e32 v15, 16, v17
	v_and_b32_e32 v16, 0xffff0000, v17
	v_mul_f32_e32 v1, v1, v9
	v_mul_f32_e32 v9, v2, v13
	v_mul_f32_e32 v2, v6, v10
	v_mul_f32_e32 v6, v3, v14
	v_mul_f32_e32 v3, v7, v11
	v_mul_f32_e32 v7, v4, v15
	v_mul_f32_e32 v4, v8, v12
	v_mul_f32_e32 v5, v5, v16
	v_cvt_pk_bf16_f32 v2, v1, v2
	v_cvt_pk_bf16_f32 v3, v3, v4
	v_cvt_pk_bf16_f32 v4, v9, v6
	v_cvt_pk_bf16_f32 v5, v7, v5
	global_store_dwordx4 v[18:19], v[2:5], off offset:1280
	s_waitcnt vmcnt(0)
	s_barrier
	s_branch .LBB0_390

.LBB0_388:
	s_barrier
	s_waitcnt vmcnt(3)
	ds_write_b128 v82, v[50:53]
	s_waitcnt vmcnt(2)
	ds_write_b128 v82, v[54:57] offset:17408
	s_waitcnt vmcnt(1)
	ds_write_b128 v80, v[58:61]
	s_waitcnt vmcnt(0)
	ds_write_b128 v80, v[62:65] offset:17408
	s_waitcnt lgkmcnt(0)
	s_barrier
	ds_read_b128 v[116:119], v83
	ds_read_b128 v[74:77], v83 offset:64
	ds_read_b128 v[70:73], v83 offset:128
	ds_read_b128 v[66:69], v83 offset:192
	s_waitcnt lgkmcnt(3)
	v_mfma_f32_16x16x32_bf16 v[116:119], v[116:119], v[30:33], 0
	v_add_u32_e32 v56, s63, v103
	v_add_u32_e32 v120, s62, v101
	v_cvt_f32_i32_e32 v122, v56
	s_waitcnt lgkmcnt(2)
	v_mfma_f32_16x16x32_bf16 v[74:77], v[74:77], v[22:25], v[116:119]
	v_cvt_f32_i32_e32 v121, v120
	v_lshl_add_u64 v[50:51], v[88:89], 0, v[84:85]
	v_mul_f32_e32 v122, v99, v122
	s_waitcnt lgkmcnt(1)
	v_mfma_f32_16x16x32_bf16 v[70:73], v[70:73], v[14:17], v[74:77]
	v_add_co_u32_e32 v54, vcc, s5, v50
	v_mul_f32_e32 v121, v90, v121
	v_exp_f32_e32 v122, v122
	v_lshl_add_u64 v[52:53], v[86:87], 0, v[84:85]
	v_addc_co_u32_e32 v55, vcc, 0, v51, vcc
	v_exp_f32_e32 v121, v121
	v_add_co_u32_e32 v62, vcc, s5, v52
	s_waitcnt lgkmcnt(0)
	v_mfma_f32_16x16x32_bf16 v[66:69], v[66:69], v[10:13], v[70:73]
	v_addc_co_u32_e32 v63, vcc, 0, v53, vcc
	v_mul_f32_e32 v133, v98, v122
	v_mul_f32_e32 v135, v96, v122
	v_cmp_ne_u32_e32 vcc, s62, v115
	v_cmp_gt_i32_e64 s[10:11], 0, v120
	v_mul_f32_e32 v132, v97, v121
	v_mul_f32_e32 v134, v95, v121
	v_mul_f32_e32 v137, v94, v122
	v_cmp_ne_u32_e64 s[6:7], s62, v114
	v_mul_f32_e32 v122, v92, v122
	v_cmp_ne_u32_e64 s[8:9], s62, v113
	v_cndmask_b32_e64 v133, 2.0, v133, s[10:11]
	v_cndmask_b32_e32 v135, 2.0, v135, vcc
	v_cmp_lt_i32_e32 vcc, 1, v120
	v_cmp_lt_i32_e64 s[36:37], 0, v120
	v_add_u32_e32 v123, -16, v120
	v_subrev_u32_e32 v125, 32, v120
	v_subrev_u32_e32 v127, 48, v120
	v_mul_f32_e32 v136, v93, v121
	v_mul_f32_e32 v121, v91, v121
	v_cndmask_b32_e64 v137, 2.0, v137, s[6:7]
	v_cmp_lt_i32_e64 s[6:7], 2, v120
	v_cndmask_b32_e64 v122, 2.0, v122, s[8:9]
	v_cmp_lt_i32_e64 s[8:9], 3, v120
	v_cndmask_b32_e64 v120, v133, v132, s[36:37]
	v_cndmask_b32_e32 v132, v135, v134, vcc
	v_cndmask_b32_e64 v133, v137, v136, s[6:7]
	v_cndmask_b32_e64 v121, v122, v121, s[8:9]
	v_mul_f32_e32 v66, v120, v66
	v_mul_f32_e32 v67, v132, v67
	v_add_u32_e32 v124, 16, v56
	v_add_u32_e32 v126, 32, v56
	v_add_u32_e32 v128, 48, v56
	global_load_dwordx4 v[50:53], v[54:55], off offset:1024
	s_nop 0
	global_load_dwordx4 v[54:57], v[54:55], off offset:2048
	s_nop 0
	global_load_dwordx4 v[58:61], v[62:63], off offset:1024
	s_nop 0
	global_load_dwordx4 v[62:65], v[62:63], off offset:2048
	v_mul_f32_e32 v68, v133, v68
	v_mul_f32_e32 v69, v121, v69
	v_cvt_pk_bf16_f32 v66, v66, v67
	v_cvt_pk_bf16_f32 v67, v68, v69
	ds_write_b64 v100, v[66:67] offset:53248
	ds_read_b128 v[66:69], v83 offset:4352
	ds_read_b128 v[70:73], v83 offset:4416
	s_waitcnt lgkmcnt(1)
	v_mfma_f32_16x16x32_bf16 v[66:69], v[66:69], v[30:33], 0
	ds_read_b128 v[74:77], v83 offset:4480
	v_cvt_f32_i32_e32 v124, v124
	v_cvt_f32_i32_e32 v129, v123
	s_waitcnt lgkmcnt(1)
	v_mfma_f32_16x16x32_bf16 v[66:69], v[70:73], v[22:25], v[66:69]
	ds_read_b128 v[70:73], v83 offset:4544
	v_mul_f32_e32 v124, v99, v124
	v_mul_f32_e32 v129, v90, v129
	s_waitcnt lgkmcnt(1)
	v_mfma_f32_16x16x32_bf16 v[66:69], v[74:77], v[14:17], v[66:69]
	v_exp_f32_e32 v124, v124
	v_exp_f32_e32 v129, v129
	v_cmp_gt_i32_e64 s[10:11], 0, v123
	s_waitcnt lgkmcnt(0)
	v_mfma_f32_16x16x32_bf16 v[66:69], v[70:73], v[10:13], v[66:69]
	v_mul_f32_e32 v139, v98, v124
	v_mul_f32_e32 v141, v96, v124
	v_cmp_ne_u32_e64 s[12:13], s62, v110
	v_mul_f32_e32 v138, v97, v129
	v_mul_f32_e32 v140, v95, v129
	v_mul_f32_e32 v143, v94, v124
	v_cmp_ne_u32_e64 s[14:15], s62, v111
	v_mul_f32_e32 v124, v92, v124
	v_cmp_ne_u32_e64 s[16:17], s62, v112
	v_cndmask_b32_e64 v122, 2.0, v139, s[10:11]
	v_cmp_lt_i32_e32 vcc, 0, v123
	v_cndmask_b32_e64 v134, 2.0, v141, s[12:13]
	v_cmp_lt_i32_e64 s[6:7], 1, v123
	v_mul_f32_e32 v142, v93, v129
	v_mul_f32_e32 v129, v91, v129
	v_cndmask_b32_e64 v135, 2.0, v143, s[14:15]
	v_cmp_lt_i32_e64 s[8:9], 2, v123
	v_cndmask_b32_e64 v124, 2.0, v124, s[16:17]
	v_cmp_lt_i32_e64 s[10:11], 3, v123
	v_cndmask_b32_e32 v117, v122, v138, vcc
	v_cndmask_b32_e64 v118, v134, v140, s[6:7]
	v_cndmask_b32_e64 v119, v135, v142, s[8:9]
	v_cndmask_b32_e64 v74, v124, v129, s[10:11]
	v_mul_f32_e32 v66, v117, v66
	v_mul_f32_e32 v67, v118, v67
	v_mul_f32_e32 v68, v119, v68
	v_mul_f32_e32 v69, v74, v69
	v_cvt_pk_bf16_f32 v66, v66, v67
	v_cvt_pk_bf16_f32 v67, v68, v69
	ds_write_b64 v100, v[66:67] offset:53280
	ds_read_b128 v[66:69], v83 offset:8704
	ds_read_b128 v[70:73], v83 offset:8768
	s_waitcnt lgkmcnt(1)
	v_mfma_f32_16x16x32_bf16 v[66:69], v[66:69], v[30:33], 0
	ds_read_b128 v[74:77], v83 offset:8832
	v_cvt_f32_i32_e32 v126, v126
	v_cvt_f32_i32_e32 v130, v125
	s_waitcnt lgkmcnt(1)
	v_mfma_f32_16x16x32_bf16 v[66:69], v[70:73], v[22:25], v[66:69]
	ds_read_b128 v[70:73], v83 offset:8896
	v_mul_f32_e32 v126, v99, v126
	v_mul_f32_e32 v130, v90, v130
	s_waitcnt lgkmcnt(1)
	v_mfma_f32_16x16x32_bf16 v[66:69], v[74:77], v[14:17], v[66:69]
	v_exp_f32_e32 v126, v126
	v_exp_f32_e32 v130, v130
	v_cmp_gt_i32_e64 s[18:19], 0, v125
	s_waitcnt lgkmcnt(0)
	v_mfma_f32_16x16x32_bf16 v[66:69], v[70:73], v[10:13], v[66:69]
	v_mul_f32_e32 v145, v98, v126
	v_mul_f32_e32 v147, v96, v126
	v_cmp_ne_u32_e64 s[20:21], s62, v107
	v_mul_f32_e32 v144, v97, v130
	v_mul_f32_e32 v146, v95, v130
	v_mul_f32_e32 v149, v94, v126
	v_cmp_ne_u32_e64 s[22:23], s62, v108
	v_mul_f32_e32 v126, v92, v126
	v_cmp_ne_u32_e64 s[24:25], s62, v109
	v_cndmask_b32_e64 v123, 2.0, v145, s[18:19]
	v_cmp_lt_i32_e64 s[12:13], 0, v125
	v_cndmask_b32_e64 v136, 2.0, v147, s[20:21]
	v_cmp_lt_i32_e64 s[14:15], 1, v125
	v_mul_f32_e32 v148, v93, v130
	v_mul_f32_e32 v130, v91, v130
	v_cndmask_b32_e64 v137, 2.0, v149, s[22:23]
	v_cmp_lt_i32_e64 s[16:17], 2, v125
	v_cndmask_b32_e64 v126, 2.0, v126, s[24:25]
	v_cmp_lt_i32_e64 s[18:19], 3, v125
	v_cndmask_b32_e64 v120, v123, v144, s[12:13]
	v_cndmask_b32_e64 v121, v136, v146, s[14:15]
	v_cndmask_b32_e64 v74, v137, v148, s[16:17]
	v_cndmask_b32_e64 v75, v126, v130, s[18:19]
	v_mul_f32_e32 v66, v120, v66
	v_mul_f32_e32 v67, v121, v67
	v_mul_f32_e32 v68, v74, v68
	v_mul_f32_e32 v69, v75, v69
	v_cvt_pk_bf16_f32 v66, v66, v67
	v_cvt_pk_bf16_f32 v67, v68, v69
	ds_write_b64 v100, v[66:67] offset:53312
	ds_read_b128 v[66:69], v83 offset:13056
	ds_read_b128 v[70:73], v83 offset:13120
	s_waitcnt lgkmcnt(1)
	v_mfma_f32_16x16x32_bf16 v[66:69], v[66:69], v[30:33], 0
	ds_read_b128 v[74:77], v83 offset:13184
	v_cvt_f32_i32_e32 v128, v128
	v_cvt_f32_i32_e32 v131, v127
	s_waitcnt lgkmcnt(1)
	v_mfma_f32_16x16x32_bf16 v[66:69], v[70:73], v[22:25], v[66:69]
	ds_read_b128 v[70:73], v83 offset:13248
	v_mul_f32_e32 v128, v99, v128
	v_mul_f32_e32 v131, v90, v131
	s_waitcnt lgkmcnt(1)
	v_mfma_f32_16x16x32_bf16 v[66:69], v[74:77], v[14:17], v[66:69]
	v_exp_f32_e32 v128, v128
	v_exp_f32_e32 v131, v131
	v_cmp_gt_i32_e64 s[26:27], 0, v127
	s_waitcnt lgkmcnt(0)
	v_mfma_f32_16x16x32_bf16 v[66:69], v[70:73], v[10:13], v[66:69]
	v_mul_f32_e32 v151, v98, v128
	v_mul_f32_e32 v153, v96, v128
	v_cmp_ne_u32_e64 s[28:29], s62, v104
	v_mul_f32_e32 v150, v97, v131
	v_mul_f32_e32 v152, v95, v131
	v_mul_f32_e32 v155, v94, v128
	v_cmp_ne_u32_e64 s[30:31], s62, v105
	v_mul_f32_e32 v128, v92, v128
	v_cmp_ne_u32_e64 s[34:35], s62, v106
	v_cndmask_b32_e64 v125, 2.0, v151, s[26:27]
	v_cmp_lt_i32_e64 s[20:21], 0, v127
	v_cndmask_b32_e64 v139, 2.0, v153, s[28:29]
	v_cmp_lt_i32_e64 s[22:23], 1, v127
	v_mul_f32_e32 v154, v93, v131
	v_mul_f32_e32 v131, v91, v131
	v_cndmask_b32_e64 v141, 2.0, v155, s[30:31]
	v_cmp_lt_i32_e64 s[24:25], 2, v127
	v_cndmask_b32_e64 v116, 2.0, v128, s[34:35]
	v_cmp_lt_i32_e64 s[26:27], 3, v127
	v_cndmask_b32_e64 v117, v125, v150, s[20:21]
	v_cndmask_b32_e64 v74, v139, v152, s[22:23]
	v_cndmask_b32_e64 v75, v141, v154, s[24:25]
	v_cndmask_b32_e64 v76, v116, v131, s[26:27]
	v_mul_f32_e32 v66, v117, v66
	v_mul_f32_e32 v67, v74, v67
	v_mul_f32_e32 v68, v75, v68
	v_mul_f32_e32 v69, v76, v69
	v_cvt_pk_bf16_f32 v66, v66, v67
	v_cvt_pk_bf16_f32 v67, v68, v69
	ds_write_b64 v100, v[66:67] offset:53344
	v_add_u32_e32 v79, v102, v78
	s_waitcnt lgkmcnt(0)
	ds_read_b128 v[66:69], v79 offset:53248
	ds_read_b128 v[70:73], v79 offset:53312
	ds_read_b64_tr_b16 v[76:77], v81 offset:18496
	ds_read_b64_tr_b16 v[74:75], v81 offset:17408
	ds_read_b64_tr_b16 v[116:117], v81 offset:17440
	ds_read_b64_tr_b16 v[120:121], v81 offset:17472
	ds_read_b64_tr_b16 v[124:125], v81 offset:17504
	ds_read_b64_tr_b16 v[118:119], v81 offset:18528
	ds_read_b64_tr_b16 v[122:123], v81 offset:18560
	ds_read_b64_tr_b16 v[126:127], v81 offset:18592
	s_waitcnt lgkmcnt(6)
	v_mfma_f32_16x16x32_bf16 v[46:49], v[66:69], v[74:77], v[46:49]
	ds_read_b64_tr_b16 v[74:75], v81 offset:17536
	ds_read_b64_tr_b16 v[76:77], v81 offset:18624
	s_add_i32 s63, s63, 64
	s_sub_i32 s62, s62, 64
	s_waitcnt lgkmcnt(4)
	v_mfma_f32_16x16x32_bf16 v[42:45], v[66:69], v[116:119], v[42:45]
	v_lshl_add_u64 v[86:87], v[86:87], 0, s[64:65]
	s_cmpk_eq_i32 s62, 0xff40
	v_lshl_add_u64 v[88:89], v[88:89], 0, s[64:65]
	s_waitcnt lgkmcnt(3)
	v_mfma_f32_16x16x32_bf16 v[38:41], v[66:69], v[120:123], v[38:41]
	ds_read_b64_tr_b16 v[116:117], v81 offset:17568
	ds_read_b64_tr_b16 v[120:121], v81 offset:17600
	ds_read_b64_tr_b16 v[128:129], v81 offset:17632
	ds_read_b64_tr_b16 v[118:119], v81 offset:18656
	ds_read_b64_tr_b16 v[122:123], v81 offset:18688
	ds_read_b64_tr_b16 v[130:131], v81 offset:18720
	s_waitcnt lgkmcnt(6)
	v_mfma_f32_16x16x32_bf16 v[26:29], v[66:69], v[74:77], v[26:29]
	ds_read_b64_tr_b16 v[74:75], v81 offset:26112
	ds_read_b64_tr_b16 v[76:77], v81 offset:27200
	v_mfma_f32_16x16x32_bf16 v[34:37], v[66:69], v[124:127], v[34:37]
	s_waitcnt lgkmcnt(4)
	v_mfma_f32_16x16x32_bf16 v[18:21], v[66:69], v[116:119], v[18:21]
	s_waitcnt lgkmcnt(3)
	v_mfma_f32_16x16x32_bf16 v[2:5], v[66:69], v[120:123], v[2:5]
	ds_read_b64_tr_b16 v[116:117], v81 offset:26144
	ds_read_b64_tr_b16 v[120:121], v81 offset:26176
	ds_read_b64_tr_b16 v[124:125], v81 offset:26208
	ds_read_b64_tr_b16 v[118:119], v81 offset:27232
	ds_read_b64_tr_b16 v[122:123], v81 offset:27264
	ds_read_b64_tr_b16 v[126:127], v81 offset:27296
	s_waitcnt lgkmcnt(8)
	v_mfma_f32_16x16x32_bf16 v[6:9], v[66:69], v[128:131], v[6:9]
	ds_read_b64_tr_b16 v[66:67], v81 offset:26240
	ds_read_b64_tr_b16 v[68:69], v81 offset:27328
	s_waitcnt lgkmcnt(8)
	v_mfma_f32_16x16x32_bf16 v[46:49], v[70:73], v[74:77], v[46:49]
	s_waitcnt lgkmcnt(4)
	v_mfma_f32_16x16x32_bf16 v[42:45], v[70:73], v[116:119], v[42:45]
	s_waitcnt lgkmcnt(3)
	v_mfma_f32_16x16x32_bf16 v[38:41], v[70:73], v[120:123], v[38:41]
	ds_read_b64_tr_b16 v[74:75], v81 offset:26272
	ds_read_b64_tr_b16 v[116:117], v81 offset:26304
	ds_read_b64_tr_b16 v[120:121], v81 offset:26336
	ds_read_b64_tr_b16 v[76:77], v81 offset:27360
	ds_read_b64_tr_b16 v[118:119], v81 offset:27392
	ds_read_b64_tr_b16 v[122:123], v81 offset:27424
	s_waitcnt lgkmcnt(8)
	v_mfma_f32_16x16x32_bf16 v[34:37], v[70:73], v[124:127], v[34:37]
	s_waitcnt lgkmcnt(6)
	v_mfma_f32_16x16x32_bf16 v[26:29], v[70:73], v[66:69], v[26:29]
	s_waitcnt lgkmcnt(2)
	v_mfma_f32_16x16x32_bf16 v[18:21], v[70:73], v[74:77], v[18:21]
	s_waitcnt lgkmcnt(1)
	v_mfma_f32_16x16x32_bf16 v[2:5], v[70:73], v[116:119], v[2:5]
	s_waitcnt lgkmcnt(0)
	v_mfma_f32_16x16x32_bf16 v[6:9], v[70:73], v[120:123], v[6:9]
	s_cbranch_scc0 .LBB0_388
	s_barrier
	s_waitcnt vmcnt(3)
	ds_write_b128 v82, v[50:53]
	s_waitcnt vmcnt(2)
	ds_write_b128 v82, v[54:57] offset:17408
	s_waitcnt vmcnt(1)
	ds_write_b128 v80, v[58:61]
	s_waitcnt vmcnt(0)
	ds_write_b128 v80, v[62:65] offset:17408
	s_waitcnt lgkmcnt(0)
	s_barrier
	ds_read_b128 v[50:53], v83
	ds_read_b128 v[54:57], v83 offset:64
	ds_read_b128 v[58:61], v83 offset:128
	ds_read_b128 v[62:65], v83 offset:192
	s_waitcnt lgkmcnt(3)
	v_mfma_f32_16x16x32_bf16 v[50:53], v[50:53], v[30:33], 0
	v_sub_u32_e32 v67, 0xc0, v101
	v_add_u32_e32 v66, 0xffffff40, v101
	v_cvt_f32_i32_e32 v66, v66
	s_waitcnt lgkmcnt(2)
	v_mfma_f32_16x16x32_bf16 v[50:53], v[54:57], v[22:25], v[50:53]
	v_cvt_f32_i32_e32 v54, v67
	s_movk_i32 s5, 0xc0
	v_mul_f32_e32 v55, v90, v66
	s_waitcnt lgkmcnt(1)
	v_mfma_f32_16x16x32_bf16 v[50:53], v[58:61], v[14:17], v[50:53]
	v_mul_f32_e32 v54, v99, v54
	v_exp_f32_e32 v54, v54
	v_exp_f32_e32 v55, v55
	s_waitcnt lgkmcnt(0)
	v_mfma_f32_16x16x32_bf16 v[50:53], v[62:65], v[10:13], v[50:53]
	v_cmp_ne_u32_e32 vcc, s5, v101
	v_mul_f32_e32 v57, v54, v98
	v_mul_f32_e32 v56, v55, v97
	v_cndmask_b32_e32 v57, 2.0, v57, vcc
	v_cmp_lt_i32_e32 vcc, s5, v101
	s_movk_i32 s5, 0xc1
	v_sub_u32_e32 v67, 0xd0, v101
	v_cndmask_b32_e32 v56, v57, v56, vcc
	v_mul_f32_e32 v57, v96, v54
	v_cmp_ne_u32_e32 vcc, s5, v101
	v_mul_f32_e32 v50, v56, v50
	v_mul_f32_e32 v56, v95, v55
	v_cndmask_b32_e32 v57, 2.0, v57, vcc
	v_cmp_lt_i32_e32 vcc, s5, v101
	s_movk_i32 s5, 0xc2
	v_add_u32_e32 v66, 0xffffff30, v101
	v_cndmask_b32_e32 v56, v57, v56, vcc
	v_mul_f32_e32 v57, v54, v94
	v_cmp_ne_u32_e32 vcc, s5, v101
	v_mul_f32_e32 v51, v56, v51
	v_mul_f32_e32 v56, v55, v93
	v_cndmask_b32_e32 v57, 2.0, v57, vcc
	v_cmp_lt_i32_e32 vcc, s5, v101
	s_movk_i32 s5, 0xc3
	v_mul_f32_e32 v54, v54, v92
	v_cndmask_b32_e32 v56, v57, v56, vcc
	v_cmp_ne_u32_e32 vcc, s5, v101
	v_mul_f32_e32 v55, v55, v91
	v_mul_f32_e32 v52, v56, v52
	v_cndmask_b32_e32 v54, 2.0, v54, vcc
	v_cmp_lt_i32_e32 vcc, s5, v101
	v_cvt_pk_bf16_f32 v50, v50, v51
	v_cvt_f32_i32_e32 v66, v66
	s_movk_i32 s5, 0xd0
	v_cndmask_b32_e32 v54, v54, v55, vcc
	v_mul_f32_e32 v53, v54, v53
	v_cvt_pk_bf16_f32 v51, v52, v53
	ds_write_b64 v100, v[50:51] offset:53248
	ds_read_b128 v[50:53], v83 offset:4352
	ds_read_b128 v[54:57], v83 offset:4416
	ds_read_b128 v[58:61], v83 offset:4480
	ds_read_b128 v[62:65], v83 offset:4544
	s_waitcnt lgkmcnt(3)
	v_mfma_f32_16x16x32_bf16 v[50:53], v[50:53], v[30:33], 0
	v_cmp_ne_u32_e32 vcc, s5, v101
	s_or_b32 s0, s1, s0
	s_add_i32 s0, s0, s3
	s_waitcnt lgkmcnt(2)
	v_mfma_f32_16x16x32_bf16 v[50:53], v[54:57], v[22:25], v[50:53]
	v_cvt_f32_i32_e32 v54, v67
	v_mul_f32_e32 v55, v90, v66
	v_exp_f32_e32 v55, v55
	s_waitcnt lgkmcnt(1)
	v_mfma_f32_16x16x32_bf16 v[50:53], v[58:61], v[14:17], v[50:53]
	v_mul_f32_e32 v54, v99, v54
	v_exp_f32_e32 v54, v54
	v_mul_f32_e32 v56, v55, v97
	s_waitcnt lgkmcnt(0)
	v_mfma_f32_16x16x32_bf16 v[50:53], v[62:65], v[10:13], v[50:53]
	v_sub_u32_e32 v67, 0xe0, v101
	v_mul_f32_e32 v57, v54, v98
	v_cndmask_b32_e32 v57, 2.0, v57, vcc
	v_cmp_lt_i32_e32 vcc, s5, v101
	s_movk_i32 s5, 0xd1
	v_add_u32_e32 v66, 0xffffff20, v101
	v_cndmask_b32_e32 v56, v57, v56, vcc
	v_mul_f32_e32 v57, v96, v54
	v_cmp_ne_u32_e32 vcc, s5, v101
	v_mul_f32_e32 v50, v56, v50
	v_mul_f32_e32 v56, v95, v55
	v_cndmask_b32_e32 v57, 2.0, v57, vcc
	v_cmp_lt_i32_e32 vcc, s5, v101
	s_movk_i32 s5, 0xd2
	v_cvt_f32_i32_e32 v66, v66
	v_cndmask_b32_e32 v56, v57, v56, vcc
	v_mul_f32_e32 v57, v54, v94
	v_cmp_ne_u32_e32 vcc, s5, v101
	v_mul_f32_e32 v51, v56, v51
	v_mul_f32_e32 v56, v55, v93
	v_cndmask_b32_e32 v57, 2.0, v57, vcc
	v_cmp_lt_i32_e32 vcc, s5, v101
	s_movk_i32 s5, 0xd3
	v_mul_f32_e32 v54, v54, v92
	v_cndmask_b32_e32 v56, v57, v56, vcc
	v_cmp_ne_u32_e32 vcc, s5, v101
	v_mul_f32_e32 v55, v55, v91
	v_mul_f32_e32 v52, v56, v52
	v_cndmask_b32_e32 v54, 2.0, v54, vcc
	v_cmp_lt_i32_e32 vcc, s5, v101
	v_cvt_pk_bf16_f32 v50, v50, v51
	s_movk_i32 s5, 0xe0
	s_mov_b32 s7, 0
	v_cndmask_b32_e32 v54, v54, v55, vcc
	v_mul_f32_e32 v53, v54, v53
	v_cvt_pk_bf16_f32 v51, v52, v53
	ds_write_b64 v100, v[50:51] offset:53280
	ds_read_b128 v[50:53], v83 offset:8704
	ds_read_b128 v[54:57], v83 offset:8768
	ds_read_b128 v[58:61], v83 offset:8832
	ds_read_b128 v[62:65], v83 offset:8896
	s_waitcnt lgkmcnt(3)
	v_mfma_f32_16x16x32_bf16 v[50:53], v[50:53], v[30:33], 0
	v_cmp_ne_u32_e32 vcc, s5, v101
	s_lshl_b32 s6, s4, 1
	s_waitcnt lgkmcnt(2)
	v_mfma_f32_16x16x32_bf16 v[50:53], v[54:57], v[22:25], v[50:53]
	v_cvt_f32_i32_e32 v54, v67
	v_mul_f32_e32 v55, v90, v66
	v_exp_f32_e32 v55, v55
	s_waitcnt lgkmcnt(1)
	v_mfma_f32_16x16x32_bf16 v[50:53], v[58:61], v[14:17], v[50:53]
	v_mul_f32_e32 v54, v99, v54
	v_exp_f32_e32 v54, v54
	v_mul_f32_e32 v56, v55, v97
	s_waitcnt lgkmcnt(0)
	v_mfma_f32_16x16x32_bf16 v[50:53], v[62:65], v[10:13], v[50:53]
	v_mul_f32_e32 v57, v54, v98
	v_cndmask_b32_e32 v57, 2.0, v57, vcc
	v_cmp_lt_i32_e32 vcc, s5, v101
	s_movk_i32 s5, 0xe1
	s_nop 0
	v_cndmask_b32_e32 v56, v57, v56, vcc
	v_mul_f32_e32 v57, v96, v54
	v_cmp_ne_u32_e32 vcc, s5, v101
	v_mul_f32_e32 v50, v56, v50
	v_mul_f32_e32 v56, v95, v55
	v_cndmask_b32_e32 v57, 2.0, v57, vcc
	v_cmp_lt_i32_e32 vcc, s5, v101
	s_movk_i32 s5, 0xe2
	s_nop 0
	v_cndmask_b32_e32 v56, v57, v56, vcc
	v_mul_f32_e32 v57, v54, v94
	v_cmp_ne_u32_e32 vcc, s5, v101
	v_mul_f32_e32 v51, v56, v51
	v_mul_f32_e32 v56, v55, v93
	v_cndmask_b32_e32 v57, 2.0, v57, vcc
	v_cmp_lt_i32_e32 vcc, s5, v101
	s_movk_i32 s5, 0xe3
	v_mul_f32_e32 v54, v54, v92
	v_cndmask_b32_e32 v56, v57, v56, vcc
	v_cmp_ne_u32_e32 vcc, s5, v101
	v_mul_f32_e32 v55, v55, v91
	v_mul_f32_e32 v52, v56, v52
	v_cndmask_b32_e32 v54, 2.0, v54, vcc
	v_cmp_lt_i32_e32 vcc, s5, v101
	v_cvt_pk_bf16_f32 v50, v50, v51
	s_movk_i32 s5, 0xf0
	s_nop 0
	v_cndmask_b32_e32 v54, v54, v55, vcc
	v_mul_f32_e32 v53, v54, v53
	v_cvt_pk_bf16_f32 v51, v52, v53
	ds_write_b64 v100, v[50:51] offset:53312
	ds_read_b128 v[50:53], v83 offset:13056
	ds_read_b128 v[54:57], v83 offset:13120
	ds_read_b128 v[58:61], v83 offset:13184
	ds_read_b128 v[62:65], v83 offset:13248
	s_waitcnt lgkmcnt(3)
	v_mfma_f32_16x16x32_bf16 v[30:33], v[50:53], v[30:33], 0
	v_sub_u32_e32 v51, 0xf0, v101
	v_add_u32_e32 v50, 0xffffff10, v101
	v_cvt_f32_i32_e32 v50, v50
	s_waitcnt lgkmcnt(2)
	v_mfma_f32_16x16x32_bf16 v[22:25], v[54:57], v[22:25], v[30:33]
	v_cmp_ne_u32_e32 vcc, s5, v101
	s_nop 1
	v_cvt_f32_i32_e32 v30, v51
	s_waitcnt lgkmcnt(1)
	v_mfma_f32_16x16x32_bf16 v[14:17], v[58:61], v[14:17], v[22:25]
	v_mul_f32_e32 v31, v90, v50
	v_mul_f32_e32 v30, v99, v30
	s_nop 0
	v_exp_f32_e32 v23, v30
	v_exp_f32_e32 v22, v31
	s_waitcnt lgkmcnt(0)
	v_mfma_f32_16x16x32_bf16 v[10:13], v[62:65], v[10:13], v[14:17]
	s_nop 2
	v_mul_f32_e32 v15, v23, v98
	v_mul_f32_e32 v14, v22, v97
	v_cndmask_b32_e32 v15, 2.0, v15, vcc
	v_cmp_lt_i32_e32 vcc, s5, v101
	s_movk_i32 s5, 0xf1
	s_nop 0
	v_cndmask_b32_e32 v14, v15, v14, vcc
	v_mul_f32_e32 v15, v96, v23
	v_cmp_ne_u32_e32 vcc, s5, v101
	v_mul_f32_e32 v10, v14, v10
	v_mul_f32_e32 v14, v95, v22
	v_cndmask_b32_e32 v15, 2.0, v15, vcc
	v_cmp_lt_i32_e32 vcc, s5, v101
	s_movk_i32 s5, 0xf2
	s_nop 0
	v_cndmask_b32_e32 v14, v15, v14, vcc
	v_mul_f32_e32 v15, v23, v94
	v_cmp_ne_u32_e32 vcc, s5, v101
	v_mul_f32_e32 v11, v14, v11
	v_mul_f32_e32 v14, v22, v93
	v_cndmask_b32_e32 v15, 2.0, v15, vcc
	v_cmp_lt_i32_e32 vcc, s5, v101
	s_movk_i32 s5, 0xf3
	v_cvt_pk_bf16_f32 v10, v10, v11
	s_nop 0
	v_cndmask_b32_e32 v14, v15, v14, vcc
	v_mul_f32_e32 v15, v23, v92
	v_cmp_ne_u32_e32 vcc, s5, v101
	v_mul_f32_e32 v12, v14, v12
	v_mul_f32_e32 v14, v22, v91
	v_cndmask_b32_e32 v15, 2.0, v15, vcc
	v_cmp_lt_i32_e32 vcc, s5, v101
	s_nop 1
	v_cndmask_b32_e32 v14, v15, v14, vcc
	v_mul_f32_e32 v13, v14, v13
	v_cvt_pk_bf16_f32 v11, v12, v13
	ds_write_b64 v100, v[10:11] offset:53344
	s_waitcnt lgkmcnt(0)
	ds_read_b128 v[54:57], v79 offset:53248
	ds_read_b128 v[50:53], v79 offset:53312
	ds_read_b64_tr_b16 v[12:13], v81 offset:18496
	ds_read_b64_tr_b16 v[10:11], v81 offset:17408
	ds_read_b64_tr_b16 v[14:15], v81 offset:17440
	ds_read_b64_tr_b16 v[58:59], v81 offset:17472
	ds_read_b64_tr_b16 v[62:63], v81 offset:17504
	ds_read_b64_tr_b16 v[16:17], v81 offset:18528
	ds_read_b64_tr_b16 v[60:61], v81 offset:18560
	ds_read_b64_tr_b16 v[64:65], v81 offset:18592
	s_waitcnt lgkmcnt(6)
	v_mfma_f32_16x16x32_bf16 v[10:13], v[54:57], v[10:13], v[46:49]
	ds_read_b64_tr_b16 v[24:25], v81 offset:27200
	ds_read_b64_tr_b16 v[22:23], v81 offset:26112
	s_nop 0
	ds_read_b64_tr_b16 v[46:47], v81 offset:26144
	ds_read_b64_tr_b16 v[66:67], v81 offset:26176
	ds_read_b64_tr_b16 v[70:71], v81 offset:26208
	ds_read_b64_tr_b16 v[48:49], v81 offset:27232
	ds_read_b64_tr_b16 v[68:69], v81 offset:27264
	ds_read_b64_tr_b16 v[72:73], v81 offset:27296
	s_waitcnt lgkmcnt(6)
	v_mfma_f32_16x16x32_bf16 v[30:33], v[50:53], v[22:25], v[10:13]
	v_mfma_f32_16x16x32_bf16 v[10:13], v[54:57], v[14:17], v[42:45]
	s_waitcnt lgkmcnt(2)
	v_mfma_f32_16x16x32_bf16 v[22:25], v[50:53], v[46:49], v[10:13]
	v_mfma_f32_16x16x32_bf16 v[10:13], v[54:57], v[58:61], v[38:41]
	s_waitcnt lgkmcnt(1)
	v_mfma_f32_16x16x32_bf16 v[14:17], v[50:53], v[66:69], v[10:13]
	v_mfma_f32_16x16x32_bf16 v[10:13], v[54:57], v[62:65], v[34:37]
	s_nop 2
	ds_read_b64_tr_b16 v[36:37], v81 offset:18624
	ds_read_b64_tr_b16 v[34:35], v81 offset:17536
	ds_read_b64_tr_b16 v[38:39], v81 offset:17568
	ds_read_b64_tr_b16 v[42:43], v81 offset:17600
	ds_read_b64_tr_b16 v[46:47], v81 offset:17632
	ds_read_b64_tr_b16 v[40:41], v81 offset:18656
	ds_read_b64_tr_b16 v[44:45], v81 offset:18688
	ds_read_b64_tr_b16 v[48:49], v81 offset:18720
	s_waitcnt lgkmcnt(6)
	v_mfma_f32_16x16x32_bf16 v[26:29], v[54:57], v[34:37], v[26:29]
	ds_read_b64_tr_b16 v[36:37], v81 offset:27328
	ds_read_b64_tr_b16 v[34:35], v81 offset:26240
	ds_read_b64_tr_b16 v[58:59], v81 offset:26272
	ds_read_b64_tr_b16 v[62:63], v81 offset:26304
	ds_read_b64_tr_b16 v[66:67], v81 offset:26336
	ds_read_b64_tr_b16 v[60:61], v81 offset:27360
	ds_read_b64_tr_b16 v[64:65], v81 offset:27392
	ds_read_b64_tr_b16 v[68:69], v81 offset:27424
	s_waitcnt lgkmcnt(6)
	v_mfma_f32_16x16x32_bf16 v[26:29], v[50:53], v[34:37], v[26:29]
	v_and_b32_e32 v34, 15, v1
	v_ashrrev_i32_e32 v1, 2, v1
	v_and_b32_e32 v1, -4, v1
	v_mfma_f32_16x16x32_bf16 v[18:21], v[54:57], v[38:41], v[18:21]
	v_add_u32_e32 v36, s0, v1
	s_movk_i32 s0, 0x1400
	v_mov_b64_e32 v[40:41], s[68:69]
	v_lshlrev_b32_e32 v38, 1, v34
	v_mad_i64_i32 v[34:35], s[4:5], v36, s0, v[40:41]
	v_mov_b32_e32 v39, 0
	v_lshl_add_u64 v[34:35], v[34:35], 0, s[6:7]
	s_waitcnt lgkmcnt(2)
	v_mfma_f32_16x16x32_bf16 v[18:21], v[50:53], v[58:61], v[18:21]
	v_lshl_add_u64 v[58:59], v[34:35], 0, v[38:39]
	v_add_f32_e32 v1, 0, v30
	v_mfma_f32_16x16x32_bf16 v[2:5], v[54:57], v[42:45], v[2:5]
	v_add_f32_e32 v1, v1, v22
	v_mfma_f32_16x16x32_bf16 v[6:9], v[54:57], v[46:49], v[6:9]
	v_mfma_f32_16x16x32_bf16 v[10:13], v[50:53], v[70:73], v[10:13]
	v_add_f32_e32 v1, v1, v14
	s_add_u32 s4, s60, s6
	s_addc_u32 s5, s61, 0
	s_waitcnt lgkmcnt(1)
	v_mfma_f32_16x16x32_bf16 v[2:5], v[50:53], v[62:65], v[2:5]
	v_lshl_add_u64 v[34:35], s[4:5], 0, v[38:39]
	s_nop 1
	v_add_f32_e32 v1, v1, v10
	v_add_f32_e32 v1, v1, v26
	s_waitcnt lgkmcnt(0)
	v_mfma_f32_16x16x32_bf16 v[6:9], v[50:53], v[66:69], v[6:9]
	v_and_b32_e32 v160, 63, v0
	v_and_b32_e32 v161, 15, v160
	v_lshrrev_b32_e32 v162, 4, v160
	v_lshrrev_b32_e32 v168, 2, v160
	v_and_b32_e32 v169, 3, v160
	v_readfirstlane_b32 s99, v36
	v_readfirstlane_b32 s98, v0
	s_lshr_b32 s98, s98, 6
	s_mul_i32 s98, s98, 0x1200
	s_add_i32 s98, s98, 0xd000
	s_add_u32 s100, s68, s6
	s_addc_u32 s101, s69, 0
	v_add_u32_e32 v171, s99, v168
	v_mul_u32_u24_e32 v172, 0x1400, v171
	v_lshl_add_u32 v172, v169, 5, v172
	v_add_u32_e32 v172, 0xc00, v172
	global_load_dwordx4 v[200:203], v172, s[100:101]
	global_load_dwordx4 v[204:207], v172, s[100:101] offset:16
	global_load_dwordx4 v[224:227], v172, s[100:101] offset:128
	global_load_dwordx4 v[228:231], v172, s[100:101] offset:144
	v_lshlrev_b32_e32 v173, 11, v171
	v_lshl_add_u32 v173, v169, 5, v173
	v_lshlrev_b32_e32 v167, 2, v162
	v_mul_u32_u24_e32 v167, 0x110, v167
	v_lshl_add_u32 v167, v161, 2, v167
	v_add_u32_e32 v167, s98, v167
	v_mul_u32_u24_e32 v170, 0x110, v168
	v_lshl_add_u32 v170, v169, 6, v170
	v_add_u32_e32 v170, s98, v170
	v_mov_b32_e32 v163, 0x3727c5ac
	s_nop 7
	v_add_f32_e32 v164, 0, v30
	v_add_f32_e32 v165, 0, v31
	v_add_f32_e32 v166, 0, v32
	v_add_f32_e32 v174, 0, v33
	v_add_f32_e32 v164, v164, v22
	v_add_f32_e32 v165, v165, v23
	v_add_f32_e32 v166, v166, v24
	v_add_f32_e32 v174, v174, v25
	v_add_f32_e32 v164, v164, v14
	v_add_f32_e32 v165, v165, v15
	v_add_f32_e32 v166, v166, v16
	v_add_f32_e32 v174, v174, v17
	v_add_f32_e32 v164, v164, v10
	v_add_f32_e32 v165, v165, v11
	v_add_f32_e32 v166, v166, v12
	v_add_f32_e32 v174, v174, v13
	v_add_f32_e32 v164, v164, v26
	v_add_f32_e32 v165, v165, v27
	v_add_f32_e32 v166, v166, v28
	v_add_f32_e32 v174, v174, v29
	v_add_f32_e32 v164, v164, v18
	v_add_f32_e32 v165, v165, v19
	v_add_f32_e32 v166, v166, v20
	v_add_f32_e32 v174, v174, v21
	v_add_f32_e32 v164, v164, v2
	v_add_f32_e32 v165, v165, v3
	v_add_f32_e32 v166, v166, v4
	v_add_f32_e32 v174, v174, v5
	v_add_f32_e32 v164, v164, v6
	v_add_f32_e32 v165, v165, v7
	v_add_f32_e32 v166, v166, v8
	v_add_f32_e32 v174, v174, v9
	v_add_f32_dpp v164, v164, v164 quad_perm:[1,0,3,2] row_mask:0xf bank_mask:0xf bound_ctrl:1
	v_add_f32_dpp v165, v165, v165 quad_perm:[1,0,3,2] row_mask:0xf bank_mask:0xf bound_ctrl:1
	v_add_f32_dpp v166, v166, v166 quad_perm:[1,0,3,2] row_mask:0xf bank_mask:0xf bound_ctrl:1
	v_add_f32_dpp v174, v174, v174 quad_perm:[1,0,3,2] row_mask:0xf bank_mask:0xf bound_ctrl:1
	v_add_f32_dpp v164, v164, v164 quad_perm:[2,3,0,1] row_mask:0xf bank_mask:0xf bound_ctrl:1
	v_add_f32_dpp v165, v165, v165 quad_perm:[2,3,0,1] row_mask:0xf bank_mask:0xf bound_ctrl:1
	v_add_f32_dpp v166, v166, v166 quad_perm:[2,3,0,1] row_mask:0xf bank_mask:0xf bound_ctrl:1
	v_add_f32_dpp v174, v174, v174 quad_perm:[2,3,0,1] row_mask:0xf bank_mask:0xf bound_ctrl:1
	v_add_f32_dpp v164, v164, v164 row_half_mirror row_mask:0xf bank_mask:0xf bound_ctrl:1
	v_add_f32_dpp v165, v165, v165 row_half_mirror row_mask:0xf bank_mask:0xf bound_ctrl:1
	v_add_f32_dpp v166, v166, v166 row_half_mirror row_mask:0xf bank_mask:0xf bound_ctrl:1
	v_add_f32_dpp v174, v174, v174 row_half_mirror row_mask:0xf bank_mask:0xf bound_ctrl:1
	v_add_f32_dpp v164, v164, v164 row_mirror row_mask:0xf bank_mask:0xf bound_ctrl:1
	v_add_f32_dpp v165, v165, v165 row_mirror row_mask:0xf bank_mask:0xf bound_ctrl:1
	v_add_f32_dpp v166, v166, v166 row_mirror row_mask:0xf bank_mask:0xf bound_ctrl:1
	v_add_f32_dpp v174, v174, v174 row_mirror row_mask:0xf bank_mask:0xf bound_ctrl:1
	v_fmamk_f32 v22, v164, 0xbc000000, v22
	v_fmamk_f32 v23, v165, 0xbc000000, v23
	v_fmamk_f32 v24, v166, 0xbc000000, v24
	v_fmamk_f32 v25, v174, 0xbc000000, v25
	v_fmamk_f32 v30, v164, 0xbc000000, v30
	v_fmamk_f32 v31, v165, 0xbc000000, v31
	v_fmamk_f32 v32, v166, 0xbc000000, v32
	v_fmamk_f32 v33, v174, 0xbc000000, v33
	v_mul_f32_e32 v175, v22, v22
	v_mul_f32_e32 v176, v23, v23
	v_mul_f32_e32 v177, v24, v24
	v_mul_f32_e32 v178, v25, v25
	v_fmac_f32_e32 v175, v30, v30
	v_fmac_f32_e32 v176, v31, v31
	v_fmac_f32_e32 v177, v32, v32
	v_fmac_f32_e32 v178, v33, v33
	v_fmamk_f32 v14, v164, 0xbc000000, v14
	v_fmamk_f32 v15, v165, 0xbc000000, v15
	v_fmamk_f32 v16, v166, 0xbc000000, v16
	v_fmamk_f32 v17, v174, 0xbc000000, v17
	v_fmac_f32_e32 v175, v14, v14
	v_fmac_f32_e32 v176, v15, v15
	v_fmac_f32_e32 v177, v16, v16
	v_fmac_f32_e32 v178, v17, v17
	v_fmamk_f32 v10, v164, 0xbc000000, v10
	v_fmamk_f32 v11, v165, 0xbc000000, v11
	v_fmamk_f32 v12, v166, 0xbc000000, v12
	v_fmamk_f32 v13, v174, 0xbc000000, v13
	v_fmac_f32_e32 v175, v10, v10
	v_fmac_f32_e32 v176, v11, v11
	v_fmac_f32_e32 v177, v12, v12
	v_fmac_f32_e32 v178, v13, v13
	v_fmamk_f32 v26, v164, 0xbc000000, v26
	v_fmamk_f32 v27, v165, 0xbc000000, v27
	v_fmamk_f32 v28, v166, 0xbc000000, v28
	v_fmamk_f32 v29, v174, 0xbc000000, v29
	v_fmac_f32_e32 v175, v26, v26
	v_fmac_f32_e32 v176, v27, v27
	v_fmac_f32_e32 v177, v28, v28
	v_fmac_f32_e32 v178, v29, v29
	v_fmamk_f32 v18, v164, 0xbc000000, v18
	v_fmamk_f32 v19, v165, 0xbc000000, v19
	v_fmamk_f32 v20, v166, 0xbc000000, v20
	v_fmamk_f32 v21, v174, 0xbc000000, v21
	v_fmac_f32_e32 v175, v18, v18
	v_fmac_f32_e32 v176, v19, v19
	v_fmac_f32_e32 v177, v20, v20
	v_fmac_f32_e32 v178, v21, v21
	v_fmamk_f32 v2, v164, 0xbc000000, v2
	v_fmamk_f32 v3, v165, 0xbc000000, v3
	v_fmamk_f32 v4, v166, 0xbc000000, v4
	v_fmamk_f32 v5, v174, 0xbc000000, v5
	v_fmac_f32_e32 v175, v2, v2
	v_fmac_f32_e32 v176, v3, v3
	v_fmac_f32_e32 v177, v4, v4
	v_fmac_f32_e32 v178, v5, v5
	v_fmamk_f32 v6, v164, 0xbc000000, v6
	v_fmamk_f32 v7, v165, 0xbc000000, v7
	v_fmamk_f32 v8, v166, 0xbc000000, v8
	v_fmamk_f32 v9, v174, 0xbc000000, v9
	v_fmac_f32_e32 v175, v6, v6
	v_fmac_f32_e32 v176, v7, v7
	v_fmac_f32_e32 v177, v8, v8
	v_fmac_f32_e32 v178, v9, v9
	v_add_f32_dpp v175, v175, v175 quad_perm:[1,0,3,2] row_mask:0xf bank_mask:0xf bound_ctrl:1
	v_add_f32_dpp v176, v176, v176 quad_perm:[1,0,3,2] row_mask:0xf bank_mask:0xf bound_ctrl:1
	v_add_f32_dpp v177, v177, v177 quad_perm:[1,0,3,2] row_mask:0xf bank_mask:0xf bound_ctrl:1
	v_add_f32_dpp v178, v178, v178 quad_perm:[1,0,3,2] row_mask:0xf bank_mask:0xf bound_ctrl:1
	v_add_f32_dpp v175, v175, v175 quad_perm:[2,3,0,1] row_mask:0xf bank_mask:0xf bound_ctrl:1
	v_add_f32_dpp v176, v176, v176 quad_perm:[2,3,0,1] row_mask:0xf bank_mask:0xf bound_ctrl:1
	v_add_f32_dpp v177, v177, v177 quad_perm:[2,3,0,1] row_mask:0xf bank_mask:0xf bound_ctrl:1
	v_add_f32_dpp v178, v178, v178 quad_perm:[2,3,0,1] row_mask:0xf bank_mask:0xf bound_ctrl:1
	v_add_f32_dpp v175, v175, v175 row_half_mirror row_mask:0xf bank_mask:0xf bound_ctrl:1
	v_add_f32_dpp v176, v176, v176 row_half_mirror row_mask:0xf bank_mask:0xf bound_ctrl:1
	v_add_f32_dpp v177, v177, v177 row_half_mirror row_mask:0xf bank_mask:0xf bound_ctrl:1
	v_add_f32_dpp v178, v178, v178 row_half_mirror row_mask:0xf bank_mask:0xf bound_ctrl:1
	v_add_f32_dpp v175, v175, v175 row_mirror row_mask:0xf bank_mask:0xf bound_ctrl:1
	v_add_f32_dpp v176, v176, v176 row_mirror row_mask:0xf bank_mask:0xf bound_ctrl:1
	v_add_f32_dpp v177, v177, v177 row_mirror row_mask:0xf bank_mask:0xf bound_ctrl:1
	v_add_f32_dpp v178, v178, v178 row_mirror row_mask:0xf bank_mask:0xf bound_ctrl:1
	v_fmamk_f32 v175, v175, 0x3c000000, v163
	v_fmamk_f32 v176, v176, 0x3c000000, v163
	v_fmamk_f32 v177, v177, 0x3c000000, v163
	v_fmamk_f32 v178, v178, 0x3c000000, v163
	v_rsq_f32_e32 v175, v175
	v_rsq_f32_e32 v176, v176
	v_rsq_f32_e32 v177, v177
	v_rsq_f32_e32 v178, v178
	s_nop 0
	v_mul_f32_e32 v30, v30, v175
	v_mul_f32_e32 v31, v31, v176
	v_mul_f32_e32 v32, v32, v177
	v_mul_f32_e32 v33, v33, v178
	v_mul_f32_e32 v22, v22, v175
	v_mul_f32_e32 v23, v23, v176
	v_mul_f32_e32 v24, v24, v177
	v_mul_f32_e32 v25, v25, v178
	v_mul_f32_e32 v14, v14, v175
	v_mul_f32_e32 v15, v15, v176
	v_mul_f32_e32 v16, v16, v177
	v_mul_f32_e32 v17, v17, v178
	v_mul_f32_e32 v10, v10, v175
	v_mul_f32_e32 v11, v11, v176
	v_mul_f32_e32 v12, v12, v177
	v_mul_f32_e32 v13, v13, v178
	v_mul_f32_e32 v26, v26, v175
	v_mul_f32_e32 v27, v27, v176
	v_mul_f32_e32 v28, v28, v177
	v_mul_f32_e32 v29, v29, v178
	v_mul_f32_e32 v18, v18, v175
	v_mul_f32_e32 v19, v19, v176
	v_mul_f32_e32 v20, v20, v177
	v_mul_f32_e32 v21, v21, v178
	v_mul_f32_e32 v2, v2, v175
	v_mul_f32_e32 v3, v3, v176
	v_mul_f32_e32 v4, v4, v177
	v_mul_f32_e32 v5, v5, v178
	v_mul_f32_e32 v6, v6, v175
	v_mul_f32_e32 v7, v7, v176
	v_mul_f32_e32 v8, v8, v177
	v_mul_f32_e32 v9, v9, v178
	ds_write_b32 v167, v30
	ds_write_b32 v167, v22 offset:64
	ds_write_b32 v167, v14 offset:128
	ds_write_b32 v167, v10 offset:192
	ds_write_b32 v167, v31 offset:272
	ds_write_b32 v167, v23 offset:336
	ds_write_b32 v167, v15 offset:400
	ds_write_b32 v167, v11 offset:464
	ds_write_b32 v167, v32 offset:544
	ds_write_b32 v167, v24 offset:608
	ds_write_b32 v167, v16 offset:672
	ds_write_b32 v167, v12 offset:736
	ds_write_b32 v167, v33 offset:816
	ds_write_b32 v167, v25 offset:880
	ds_write_b32 v167, v17 offset:944
	ds_write_b32 v167, v13 offset:1008
	s_waitcnt lgkmcnt(0)
	ds_read_b128 v[184:187], v170
	ds_read_b128 v[188:191], v170 offset:16
	ds_read_b128 v[192:195], v170 offset:32
	ds_read_b128 v[196:199], v170 offset:48
	s_waitcnt vmcnt(2) lgkmcnt(0)
	v_lshlrev_b32_e32 v220, 16, v200
	v_and_b32_e32 v221, 0xffff0000, v200
	v_lshlrev_b32_e32 v222, 16, v201
	v_and_b32_e32 v223, 0xffff0000, v201
	v_mul_f32_e32 v232, 0xbfb8aa3b, v220
	v_mul_f32_e32 v233, 0xbfb8aa3b, v221
	v_mul_f32_e32 v234, 0xbfb8aa3b, v222
	v_mul_f32_e32 v235, 0xbfb8aa3b, v223
	v_exp_f32_e32 v232, v232
	v_exp_f32_e32 v233, v233
	v_exp_f32_e32 v234, v234
	v_exp_f32_e32 v235, v235
	s_nop 0
	v_add_f32_e32 v232, 1.0, v232
	v_add_f32_e32 v233, 1.0, v233
	v_add_f32_e32 v234, 1.0, v234
	v_add_f32_e32 v235, 1.0, v235
	v_rcp_f32_e32 v232, v232
	v_rcp_f32_e32 v233, v233
	v_rcp_f32_e32 v234, v234
	v_rcp_f32_e32 v235, v235
	s_nop 0
	v_mul_f32_e32 v220, v232, v220
	v_mul_f32_e32 v221, v233, v221
	v_mul_f32_e32 v222, v234, v222
	v_mul_f32_e32 v223, v235, v223
	v_mul_f32_e32 v220, v220, v184
	v_mul_f32_e32 v221, v221, v185
	v_mul_f32_e32 v222, v222, v186
	v_mul_f32_e32 v223, v223, v187
	v_cvt_pk_bf16_f32 v208, v220, v221
	v_cvt_pk_bf16_f32 v209, v222, v223
	v_lshlrev_b32_e32 v220, 16, v202
	v_and_b32_e32 v221, 0xffff0000, v202
	v_lshlrev_b32_e32 v222, 16, v203
	v_and_b32_e32 v223, 0xffff0000, v203
	v_mul_f32_e32 v232, 0xbfb8aa3b, v220
	v_mul_f32_e32 v233, 0xbfb8aa3b, v221
	v_mul_f32_e32 v234, 0xbfb8aa3b, v222
	v_mul_f32_e32 v235, 0xbfb8aa3b, v223
	v_exp_f32_e32 v232, v232
	v_exp_f32_e32 v233, v233
	v_exp_f32_e32 v234, v234
	v_exp_f32_e32 v235, v235
	s_nop 0
	v_add_f32_e32 v232, 1.0, v232
	v_add_f32_e32 v233, 1.0, v233
	v_add_f32_e32 v234, 1.0, v234
	v_add_f32_e32 v235, 1.0, v235
	v_rcp_f32_e32 v232, v232
	v_rcp_f32_e32 v233, v233
	v_rcp_f32_e32 v234, v234
	v_rcp_f32_e32 v235, v235
	s_nop 0
	v_mul_f32_e32 v220, v232, v220
	v_mul_f32_e32 v221, v233, v221
	v_mul_f32_e32 v222, v234, v222
	v_mul_f32_e32 v223, v235, v223
	v_mul_f32_e32 v220, v220, v188
	v_mul_f32_e32 v221, v221, v189
	v_mul_f32_e32 v222, v222, v190
	v_mul_f32_e32 v223, v223, v191
	v_cvt_pk_bf16_f32 v210, v220, v221
	v_cvt_pk_bf16_f32 v211, v222, v223
	v_lshlrev_b32_e32 v220, 16, v204
	v_and_b32_e32 v221, 0xffff0000, v204
	v_lshlrev_b32_e32 v222, 16, v205
	v_and_b32_e32 v223, 0xffff0000, v205
	v_mul_f32_e32 v232, 0xbfb8aa3b, v220
	v_mul_f32_e32 v233, 0xbfb8aa3b, v221
	v_mul_f32_e32 v234, 0xbfb8aa3b, v222
	v_mul_f32_e32 v235, 0xbfb8aa3b, v223
	v_exp_f32_e32 v232, v232
	v_exp_f32_e32 v233, v233
	v_exp_f32_e32 v234, v234
	v_exp_f32_e32 v235, v235
	s_nop 0
	v_add_f32_e32 v232, 1.0, v232
	v_add_f32_e32 v233, 1.0, v233
	v_add_f32_e32 v234, 1.0, v234
	v_add_f32_e32 v235, 1.0, v235
	v_rcp_f32_e32 v232, v232
	v_rcp_f32_e32 v233, v233
	v_rcp_f32_e32 v234, v234
	v_rcp_f32_e32 v235, v235
	s_nop 0
	v_mul_f32_e32 v220, v232, v220
	v_mul_f32_e32 v221, v233, v221
	v_mul_f32_e32 v222, v234, v222
	v_mul_f32_e32 v223, v235, v223
	v_mul_f32_e32 v220, v220, v192
	v_mul_f32_e32 v221, v221, v193
	v_mul_f32_e32 v222, v222, v194
	v_mul_f32_e32 v223, v223, v195
	v_cvt_pk_bf16_f32 v216, v220, v221
	v_cvt_pk_bf16_f32 v217, v222, v223
	v_lshlrev_b32_e32 v220, 16, v206
	v_and_b32_e32 v221, 0xffff0000, v206
	v_lshlrev_b32_e32 v222, 16, v207
	v_and_b32_e32 v223, 0xffff0000, v207
	v_mul_f32_e32 v232, 0xbfb8aa3b, v220
	v_mul_f32_e32 v233, 0xbfb8aa3b, v221
	v_mul_f32_e32 v234, 0xbfb8aa3b, v222
	v_mul_f32_e32 v235, 0xbfb8aa3b, v223
	v_exp_f32_e32 v232, v232
	v_exp_f32_e32 v233, v233
	v_exp_f32_e32 v234, v234
	v_exp_f32_e32 v235, v235
	s_nop 0
	v_add_f32_e32 v232, 1.0, v232
	v_add_f32_e32 v233, 1.0, v233
	v_add_f32_e32 v234, 1.0, v234
	v_add_f32_e32 v235, 1.0, v235
	v_rcp_f32_e32 v232, v232
	v_rcp_f32_e32 v233, v233
	v_rcp_f32_e32 v234, v234
	v_rcp_f32_e32 v235, v235
	s_nop 0
	v_mul_f32_e32 v220, v232, v220
	v_mul_f32_e32 v221, v233, v221
	v_mul_f32_e32 v222, v234, v222
	v_mul_f32_e32 v223, v235, v223
	v_mul_f32_e32 v220, v220, v196
	v_mul_f32_e32 v221, v221, v197
	v_mul_f32_e32 v222, v222, v198
	v_mul_f32_e32 v223, v223, v199
	v_cvt_pk_bf16_f32 v218, v220, v221
	v_cvt_pk_bf16_f32 v219, v222, v223
	global_store_dwordx4 v173, v[208:211], s[4:5]
	global_store_dwordx4 v173, v[216:219], s[4:5] offset:16
	ds_write_b32 v167, v26
	ds_write_b32 v167, v18 offset:64
	ds_write_b32 v167, v2 offset:128
	ds_write_b32 v167, v6 offset:192
	ds_write_b32 v167, v27 offset:272
	ds_write_b32 v167, v19 offset:336
	ds_write_b32 v167, v3 offset:400
	ds_write_b32 v167, v7 offset:464
	ds_write_b32 v167, v28 offset:544
	ds_write_b32 v167, v20 offset:608
	ds_write_b32 v167, v4 offset:672
	ds_write_b32 v167, v8 offset:736
	ds_write_b32 v167, v29 offset:816
	ds_write_b32 v167, v21 offset:880
	ds_write_b32 v167, v5 offset:944
	ds_write_b32 v167, v9 offset:1008
	s_waitcnt lgkmcnt(0)
	ds_read_b128 v[184:187], v170
	ds_read_b128 v[188:191], v170 offset:16
	ds_read_b128 v[192:195], v170 offset:32
	ds_read_b128 v[196:199], v170 offset:48
	s_waitcnt vmcnt(2) lgkmcnt(0)
	v_lshlrev_b32_e32 v220, 16, v224
	v_and_b32_e32 v221, 0xffff0000, v224
	v_lshlrev_b32_e32 v222, 16, v225
	v_and_b32_e32 v223, 0xffff0000, v225
	v_mul_f32_e32 v232, 0xbfb8aa3b, v220
	v_mul_f32_e32 v233, 0xbfb8aa3b, v221
	v_mul_f32_e32 v234, 0xbfb8aa3b, v222
	v_mul_f32_e32 v235, 0xbfb8aa3b, v223
	v_exp_f32_e32 v232, v232
	v_exp_f32_e32 v233, v233
	v_exp_f32_e32 v234, v234
	v_exp_f32_e32 v235, v235
	s_nop 0
	v_add_f32_e32 v232, 1.0, v232
	v_add_f32_e32 v233, 1.0, v233
	v_add_f32_e32 v234, 1.0, v234
	v_add_f32_e32 v235, 1.0, v235
	v_rcp_f32_e32 v232, v232
	v_rcp_f32_e32 v233, v233
	v_rcp_f32_e32 v234, v234
	v_rcp_f32_e32 v235, v235
	s_nop 0
	v_mul_f32_e32 v220, v232, v220
	v_mul_f32_e32 v221, v233, v221
	v_mul_f32_e32 v222, v234, v222
	v_mul_f32_e32 v223, v235, v223
	v_mul_f32_e32 v220, v220, v184
	v_mul_f32_e32 v221, v221, v185
	v_mul_f32_e32 v222, v222, v186
	v_mul_f32_e32 v223, v223, v187
	v_cvt_pk_bf16_f32 v208, v220, v221
	v_cvt_pk_bf16_f32 v209, v222, v223
	v_lshlrev_b32_e32 v220, 16, v226
	v_and_b32_e32 v221, 0xffff0000, v226
	v_lshlrev_b32_e32 v222, 16, v227
	v_and_b32_e32 v223, 0xffff0000, v227
	v_mul_f32_e32 v232, 0xbfb8aa3b, v220
	v_mul_f32_e32 v233, 0xbfb8aa3b, v221
	v_mul_f32_e32 v234, 0xbfb8aa3b, v222
	v_mul_f32_e32 v235, 0xbfb8aa3b, v223
	v_exp_f32_e32 v232, v232
	v_exp_f32_e32 v233, v233
	v_exp_f32_e32 v234, v234
	v_exp_f32_e32 v235, v235
	s_nop 0
	v_add_f32_e32 v232, 1.0, v232
	v_add_f32_e32 v233, 1.0, v233
	v_add_f32_e32 v234, 1.0, v234
	v_add_f32_e32 v235, 1.0, v235
	v_rcp_f32_e32 v232, v232
	v_rcp_f32_e32 v233, v233
	v_rcp_f32_e32 v234, v234
	v_rcp_f32_e32 v235, v235
	s_nop 0
	v_mul_f32_e32 v220, v232, v220
	v_mul_f32_e32 v221, v233, v221
	v_mul_f32_e32 v222, v234, v222
	v_mul_f32_e32 v223, v235, v223
	v_mul_f32_e32 v220, v220, v188
	v_mul_f32_e32 v221, v221, v189
	v_mul_f32_e32 v222, v222, v190
	v_mul_f32_e32 v223, v223, v191
	v_cvt_pk_bf16_f32 v210, v220, v221
	v_cvt_pk_bf16_f32 v211, v222, v223
	v_lshlrev_b32_e32 v220, 16, v228
	v_and_b32_e32 v221, 0xffff0000, v228
	v_lshlrev_b32_e32 v222, 16, v229
	v_and_b32_e32 v223, 0xffff0000, v229
	v_mul_f32_e32 v232, 0xbfb8aa3b, v220
	v_mul_f32_e32 v233, 0xbfb8aa3b, v221
	v_mul_f32_e32 v234, 0xbfb8aa3b, v222
	v_mul_f32_e32 v235, 0xbfb8aa3b, v223
	v_exp_f32_e32 v232, v232
	v_exp_f32_e32 v233, v233
	v_exp_f32_e32 v234, v234
	v_exp_f32_e32 v235, v235
	s_nop 0
	v_add_f32_e32 v232, 1.0, v232
	v_add_f32_e32 v233, 1.0, v233
	v_add_f32_e32 v234, 1.0, v234
	v_add_f32_e32 v235, 1.0, v235
	v_rcp_f32_e32 v232, v232
	v_rcp_f32_e32 v233, v233
	v_rcp_f32_e32 v234, v234
	v_rcp_f32_e32 v235, v235
	s_nop 0
	v_mul_f32_e32 v220, v232, v220
	v_mul_f32_e32 v221, v233, v221
	v_mul_f32_e32 v222, v234, v222
	v_mul_f32_e32 v223, v235, v223
	v_mul_f32_e32 v220, v220, v192
	v_mul_f32_e32 v221, v221, v193
	v_mul_f32_e32 v222, v222, v194
	v_mul_f32_e32 v223, v223, v195
	v_cvt_pk_bf16_f32 v216, v220, v221
	v_cvt_pk_bf16_f32 v217, v222, v223
	v_lshlrev_b32_e32 v220, 16, v230
	v_and_b32_e32 v221, 0xffff0000, v230
	v_lshlrev_b32_e32 v222, 16, v231
	v_and_b32_e32 v223, 0xffff0000, v231
	v_mul_f32_e32 v232, 0xbfb8aa3b, v220
	v_mul_f32_e32 v233, 0xbfb8aa3b, v221
	v_mul_f32_e32 v234, 0xbfb8aa3b, v222
	v_mul_f32_e32 v235, 0xbfb8aa3b, v223
	v_exp_f32_e32 v232, v232
	v_exp_f32_e32 v233, v233
	v_exp_f32_e32 v234, v234
	v_exp_f32_e32 v235, v235
	s_nop 0
	v_add_f32_e32 v232, 1.0, v232
	v_add_f32_e32 v233, 1.0, v233
	v_add_f32_e32 v234, 1.0, v234
	v_add_f32_e32 v235, 1.0, v235
	v_rcp_f32_e32 v232, v232
	v_rcp_f32_e32 v233, v233
	v_rcp_f32_e32 v234, v234
	v_rcp_f32_e32 v235, v235
	s_nop 0
	v_mul_f32_e32 v220, v232, v220
	v_mul_f32_e32 v221, v233, v221
	v_mul_f32_e32 v222, v234, v222
	v_mul_f32_e32 v223, v235, v223
	v_mul_f32_e32 v220, v220, v196
	v_mul_f32_e32 v221, v221, v197
	v_mul_f32_e32 v222, v222, v198
	v_mul_f32_e32 v223, v223, v199
	v_cvt_pk_bf16_f32 v218, v220, v221
	v_cvt_pk_bf16_f32 v219, v222, v223
	global_store_dwordx4 v173, v[208:211], s[4:5] offset:128
	global_store_dwordx4 v173, v[216:219], s[4:5] offset:144
	s_add_i32 s3, s38, 0xffffff80
	s_cmpk_gt_i32 s38, 0x7f
	s_cselect_b32 s1, s3, 0x100000
	s_mov_b32 s98, s1
	v_mov_b32_e32 v13, v0
	v_readlane_b32 s94, v242, 40
	s_cmpk_gt_u32 s1, 0x7f
	v_readfirstlane_b32 s0, v13
	v_readlane_b32 s95, v242, 41
	s_waitcnt vmcnt(0) lgkmcnt(0)
	s_nop 3
	s_and_saveexec_b64 s[100:101], s[94:95]
	s_cbranch_execz .Lp5_late_done
	s_getreg_b32 s99, hwreg(HW_REG_XCC_ID, 0, 4)
	s_lshl_b32 s99, s99, 8
	v_mov_b32_e32 v1, s99
	v_add_u32_e32 v1, 0x6400, v1
	v_mov_b32_e32 v2, 3
	s_mov_b32 s99, 0
.Lp5_late_spin:
	global_load_dword v3, v1, s[54:55] sc1
	s_waitcnt vmcnt(0)
	v_cmp_ge_u32_e32 vcc, v3, v2
	s_cbranch_vccnz .Lp5_late_done
	s_add_i32 s99, s99, 1
	s_cmp_gt_u32 s99, 0x40000
	s_cbranch_scc1 .Lp5_late_done
	s_sleep 1
	s_branch .Lp5_late_spin
.Lp5_late_done:
	s_or_b64 exec, exec, s[100:101]
	s_barrier
	s_branch .Lp5_glu
